# attention tile bodies rewritten by hand: ring-buffered K/V LDS reads with counted waits, permlane max, no per-MFMA branches
# speedup vs baseline: 1.0042x; 1.0042x over previous
.LBB0_235:
	s_cmp_ge_u32 s74, s93
	s_cselect_b64 s[8:9], -1, 0
	s_cmp_le_u32 s74, s20
	s_cselect_b64 s[10:11], -1, 0
	s_and_b64 s[12:13], s[8:9], s[10:11]
	s_cmp_gt_u32 s74, s93
	s_cselect_b64 s[10:11], -1, 0
	s_cmp_le_u32 s74, s21
	s_cselect_b64 s[28:29], -1, 0
	s_and_b64 s[10:11], s[10:11], s[28:29]
	s_or_b64 s[28:29], s[12:13], s[10:11]
	s_andn2_b64 vcc, exec, s[28:29]
	s_cbranch_vccnz .LBB0_239
	s_and_b64 s[28:29], s[12:13], s[10:11]
	s_cbranch_scc1 .Latt_t1_ab
	s_and_b64 vcc, exec, s[12:13]
	s_cbranch_vccnz .Latt_t1_a
	s_branch .Latt_t1_b

; __device__ __forceinline__ void attn_softmax(f32x4 (&sc)[4], float& m_run, float& l_run, f32x4 (&o)[8], const int j, const int tq, const int g, const LAS float* tb, bf16x8 (&pb)[2]) {
;     ...
;     if (j <= 5) { const float bc = tb[256];
; #pragma unroll
;         for (int mt = 0; mt < 4; ++mt)
; #pragma unroll
;             for (int e = 0; e < 4; ++e) { sc[mt][e] = sc[mt][e] * SC + bc; mx = fmaxf(mx, sc[mt][e]); } }
;     else { const int relb = tq + 64 * (8 - j) - 4 * g;
; #pragma unroll
;         for (int mt = 0; mt < 4; ++mt)
; #pragma unroll
;             for (int e = 0; e < 4; ++e) { int rel = relb - 16 * mt - e; rel = rel > 128 ? 128 : rel; sc[mt][e] = sc[mt][e] * SC + tb[rel + 128]; mx = fmaxf(mx, sc[mt][e]); } }
.Latt_t1_ab:
	s_sub_i32 s36, s74, s93
	s_add_i32 s37, s36, -1
	v_add_u32_e32 v164, v187, v189
	v_add_u32_e32 v165, v187, v190
	v_add_u32_e32 v166, v187, v191
	ds_read_b128 v[218:221], v211
	ds_read_b128 v[222:225], v164
	ds_read_b128 v[226:229], v165
	ds_read_b128 v[230:233], v166
	ds_read_b128 v[234:237], v211 offset:4096
	ds_read_b128 v[238:241], v164 offset:4096
	ds_read_b128 v[242:245], v165 offset:4096
	ds_read_b128 v[246:249], v166 offset:4096
	s_waitcnt lgkmcnt(7)
	v_mfma_f32_16x16x32_bf16 v[132:135], v[218:221], v[4:7], 0
	v_mfma_f32_16x16x32_bf16 v[148:151], v[218:221], v[8:11], 0
	ds_read_b128 v[218:221], v211 offset:8192
	s_waitcnt lgkmcnt(7)
	v_mfma_f32_16x16x32_bf16 v[132:135], v[222:225], v[12:15], v[132:135]
	v_mfma_f32_16x16x32_bf16 v[148:151], v[222:225], v[16:19], v[148:151]
	ds_read_b128 v[222:225], v164 offset:8192
	s_waitcnt lgkmcnt(7)
	v_mfma_f32_16x16x32_bf16 v[132:135], v[226:229], v[20:23], v[132:135]
	v_mfma_f32_16x16x32_bf16 v[148:151], v[226:229], v[24:27], v[148:151]
	ds_read_b128 v[226:229], v165 offset:8192
	s_waitcnt lgkmcnt(7)
	v_mfma_f32_16x16x32_bf16 v[132:135], v[230:233], v[28:31], v[132:135]
	v_mfma_f32_16x16x32_bf16 v[148:151], v[230:233], v[32:35], v[148:151]
	ds_read_b128 v[230:233], v166 offset:8192
	s_waitcnt lgkmcnt(7)
	v_mfma_f32_16x16x32_bf16 v[136:139], v[234:237], v[4:7], 0
	v_mfma_f32_16x16x32_bf16 v[152:155], v[234:237], v[8:11], 0
	ds_read_b128 v[234:237], v211 offset:12288
	s_waitcnt lgkmcnt(7)
	v_mfma_f32_16x16x32_bf16 v[136:139], v[238:241], v[12:15], v[136:139]
	v_mfma_f32_16x16x32_bf16 v[152:155], v[238:241], v[16:19], v[152:155]
	ds_read_b128 v[238:241], v164 offset:12288
	s_waitcnt lgkmcnt(7)
	v_mfma_f32_16x16x32_bf16 v[136:139], v[242:245], v[20:23], v[136:139]
	v_mfma_f32_16x16x32_bf16 v[152:155], v[242:245], v[24:27], v[152:155]
	ds_read_b128 v[242:245], v165 offset:12288
	s_waitcnt lgkmcnt(7)
	v_mfma_f32_16x16x32_bf16 v[136:139], v[246:249], v[28:31], v[136:139]
	v_mfma_f32_16x16x32_bf16 v[152:155], v[246:249], v[32:35], v[152:155]
	ds_read_b128 v[246:249], v166 offset:12288
	s_waitcnt lgkmcnt(7)
	v_mfma_f32_16x16x32_bf16 v[140:143], v[218:221], v[4:7], 0
	v_mfma_f32_16x16x32_bf16 v[156:159], v[218:221], v[8:11], 0
	s_waitcnt lgkmcnt(6)
	v_mfma_f32_16x16x32_bf16 v[140:143], v[222:225], v[12:15], v[140:143]
	v_mfma_f32_16x16x32_bf16 v[156:159], v[222:225], v[16:19], v[156:159]
	s_waitcnt lgkmcnt(5)
	v_mfma_f32_16x16x32_bf16 v[140:143], v[226:229], v[20:23], v[140:143]
	v_mfma_f32_16x16x32_bf16 v[156:159], v[226:229], v[24:27], v[156:159]
	s_waitcnt lgkmcnt(4)
	v_mfma_f32_16x16x32_bf16 v[140:143], v[230:233], v[28:31], v[140:143]
	v_mfma_f32_16x16x32_bf16 v[156:159], v[230:233], v[32:35], v[156:159]
	s_waitcnt lgkmcnt(0)
	s_cmp_gt_i32 s36, 5
	s_cbranch_scc0 .Latt_t1_ab_bc_a_const
	s_mov_b32 s38, 0x10100
	v_lshl_add_u32 v1, v210, 2, s38
	v_min_i32_e32 v218, 0x10400, v1
	v_add_u32_e32 v219, 0xfffffffc, v1
	v_min_i32_e32 v219, 0x10400, v219
	v_add_u32_e32 v220, 0xfffffff8, v1
	v_min_i32_e32 v220, 0x10400, v220
	v_add_u32_e32 v221, 0xfffffff4, v1
	v_min_i32_e32 v221, 0x10400, v221
	v_add_u32_e32 v222, 0xffffffc0, v1
	v_min_i32_e32 v222, 0x10400, v222
	v_add_u32_e32 v223, 0xffffffbc, v1
	v_min_i32_e32 v223, 0x10400, v223
	v_add_u32_e32 v224, 0xffffffb8, v1
	v_min_i32_e32 v224, 0x10400, v224
	v_add_u32_e32 v225, 0xffffffb4, v1
	v_min_i32_e32 v225, 0x10400, v225
	v_add_u32_e32 v226, 0xffffff80, v1
	v_min_i32_e32 v226, 0x10400, v226
	v_add_u32_e32 v227, 0xffffff7c, v1
	v_min_i32_e32 v227, 0x10400, v227
	v_add_u32_e32 v228, 0xffffff78, v1
	v_min_i32_e32 v228, 0x10400, v228
	v_add_u32_e32 v229, 0xffffff74, v1
	v_min_i32_e32 v229, 0x10400, v229
	v_add_u32_e32 v230, 0xffffff40, v1
	v_min_i32_e32 v230, 0x10400, v230
	v_add_u32_e32 v231, 0xffffff3c, v1
	v_min_i32_e32 v231, 0x10400, v231
	v_add_u32_e32 v232, 0xffffff38, v1
	v_min_i32_e32 v232, 0x10400, v232
	v_add_u32_e32 v233, 0xffffff34, v1
	v_min_i32_e32 v233, 0x10400, v233
	ds_read_b32 v218, v218
	ds_read_b32 v219, v219
	ds_read_b32 v220, v220
	ds_read_b32 v221, v221
	ds_read_b32 v222, v222
	ds_read_b32 v223, v223
	ds_read_b32 v224, v224
	ds_read_b32 v225, v225
	ds_read_b32 v226, v226
	ds_read_b32 v227, v227
	ds_read_b32 v228, v228
	ds_read_b32 v229, v229
	ds_read_b32 v230, v230
	ds_read_b32 v231, v231
	ds_read_b32 v232, v232
	ds_read_b32 v233, v233
	s_branch .Latt_t1_ab_bc_a_done
.Latt_t1_ab_bc_a_const:
	v_mov_b32_e32 v1, s59
	ds_read_b32 v218, v1
.Latt_t1_ab_bc_a_done:
	v_mfma_f32_16x16x32_bf16 v[144:147], v[234:237], v[4:7], 0
	v_mfma_f32_16x16x32_bf16 v[160:163], v[234:237], v[8:11], 0
	v_mfma_f32_16x16x32_bf16 v[144:147], v[238:241], v[12:15], v[144:147]
	v_mfma_f32_16x16x32_bf16 v[160:163], v[238:241], v[16:19], v[160:163]
	v_mfma_f32_16x16x32_bf16 v[144:147], v[242:245], v[20:23], v[144:147]
	v_mfma_f32_16x16x32_bf16 v[160:163], v[242:245], v[24:27], v[160:163]
	v_mfma_f32_16x16x32_bf16 v[144:147], v[246:249], v[28:31], v[144:147]
	v_mfma_f32_16x16x32_bf16 v[160:163], v[246:249], v[32:35], v[160:163]
	s_waitcnt lgkmcnt(0)
	s_cmp_gt_i32 s37, 5
	s_cbranch_scc0 .Latt_t1_ab_bc_b_const
	s_mov_b32 s38, 0x10200
	v_lshl_add_u32 v1, v210, 2, s38
	v_min_i32_e32 v234, 0x10400, v1
	v_add_u32_e32 v235, 0xfffffffc, v1
	v_min_i32_e32 v235, 0x10400, v235
	v_add_u32_e32 v236, 0xfffffff8, v1
	v_min_i32_e32 v236, 0x10400, v236
	v_add_u32_e32 v237, 0xfffffff4, v1
	v_min_i32_e32 v237, 0x10400, v237
	v_add_u32_e32 v238, 0xffffffc0, v1
	v_min_i32_e32 v238, 0x10400, v238
	v_add_u32_e32 v239, 0xffffffbc, v1
	v_min_i32_e32 v239, 0x10400, v239
	v_add_u32_e32 v240, 0xffffffb8, v1
	v_min_i32_e32 v240, 0x10400, v240
	v_add_u32_e32 v241, 0xffffffb4, v1
	v_min_i32_e32 v241, 0x10400, v241
	v_add_u32_e32 v242, 0xffffff80, v1
	v_min_i32_e32 v242, 0x10400, v242
	v_add_u32_e32 v243, 0xffffff7c, v1
	v_min_i32_e32 v243, 0x10400, v243
	v_add_u32_e32 v244, 0xffffff78, v1
	v_min_i32_e32 v244, 0x10400, v244
	v_add_u32_e32 v245, 0xffffff74, v1
	v_min_i32_e32 v245, 0x10400, v245
	v_add_u32_e32 v246, 0xffffff40, v1
	v_min_i32_e32 v246, 0x10400, v246
	v_add_u32_e32 v247, 0xffffff3c, v1
	v_min_i32_e32 v247, 0x10400, v247
	v_add_u32_e32 v248, 0xffffff38, v1
	v_min_i32_e32 v248, 0x10400, v248
	v_add_u32_e32 v249, 0xffffff34, v1
	v_min_i32_e32 v249, 0x10400, v249
	ds_read_b32 v234, v234
	ds_read_b32 v235, v235
	ds_read_b32 v236, v236
	ds_read_b32 v237, v237
	ds_read_b32 v238, v238
	ds_read_b32 v239, v239
	ds_read_b32 v240, v240
	ds_read_b32 v241, v241
	ds_read_b32 v242, v242
	ds_read_b32 v243, v243
	ds_read_b32 v244, v244
	ds_read_b32 v245, v245
	ds_read_b32 v246, v246
	ds_read_b32 v247, v247
	ds_read_b32 v248, v248
	ds_read_b32 v249, v249
	s_branch .Latt_t1_ab_bc_b_done
; __device__ __forceinline__ unsigned cvt_pk_bf16(float lo, float hi) { unsigned r; asm volatile("v_cvt_pk_bf16_f32 %0, %1, %2" : "=v"(r) : "v"(lo), "v"(hi)); return r; }
; __device__ __forceinline__ void attn_softmax(f32x4 (&sc)[4], float& m_run, float& l_run, f32x4 (&o)[8], const int j, const int tq, const int g, const LAS float* tb, bf16x8 (&pb)[2]) {
;     ...
;     if (j <= 5) { const float bc = tb[256];
; #pragma unroll
;         for (int mt = 0; mt < 4; ++mt)
; #pragma unroll
;             for (int e = 0; e < 4; ++e) { sc[mt][e] = sc[mt][e] * SC + bc; mx = fmaxf(mx, sc[mt][e]); } }
;     else { const int relb = tq + 64 * (8 - j) - 4 * g;
; #pragma unroll
;         for (int mt = 0; mt < 4; ++mt)
; #pragma unroll
;             for (int e = 0; e < 4; ++e) { int rel = relb - 16 * mt - e; rel = rel > 128 ? 128 : rel; sc[mt][e] = sc[mt][e] * SC + tb[rel + 128]; mx = fmaxf(mx, sc[mt][e]); } }
;     mx = fmaxf(mx, __shfl_xor(mx, 16)); mx = fmaxf(mx, __shfl_xor(mx, 32));
;     const float alpha = __builtin_amdgcn_exp2f(m_run - mx); m_run = mx;
;     float ls = 0.f;
; #pragma unroll
;     for (int mt = 0; mt < 4; ++mt)
; #pragma unroll
;         for (int e = 0; e < 4; ++e) { sc[mt][e] = __builtin_amdgcn_exp2f(sc[mt][e] - mx); ls += sc[mt][e]; }
;     l_run = l_run * alpha + ls;
;     if (__builtin_amdgcn_ballot_w64(alpha != 1.0f) != 0ull) {
; #pragma unroll
;         for (int cc = 0; cc < 8; ++cc) o[cc] *= alpha;
;     }
; #pragma unroll
;     for (int s2 = 0; s2 < 2; ++s2) { u32x4 pw; pw.x = cvt_pk_bf16(sc[2 * s2][0], sc[2 * s2][1]); pw.y = cvt_pk_bf16(sc[2 * s2][2], sc[2 * s2][3]);
;         pw.z = cvt_pk_bf16(sc[2 * s2 + 1][0], sc[2 * s2 + 1][1]); pw.w = cvt_pk_bf16(sc[2 * s2 + 1][2], sc[2 * s2 + 1][3]); pb[s2] = __builtin_bit_cast(bf16x8, pw); }
.Latt_t1_ab_bc_b_const:
	v_mov_b32_e32 v1, s59
	ds_read_b32 v234, v1
.Latt_t1_ab_bc_b_done:
	s_nop 7
	s_cmp_gt_i32 s36, 5
	s_cbranch_scc0 .Latt_t1_ab_sm_a_cfma
	v_pk_fma_f32 v[132:133], v[132:133], s[44:45], v[218:219] op_sel_hi:[1,0,1]
	v_pk_fma_f32 v[134:135], v[134:135], s[44:45], v[220:221] op_sel_hi:[1,0,1]
	v_pk_fma_f32 v[136:137], v[136:137], s[44:45], v[222:223] op_sel_hi:[1,0,1]
	v_pk_fma_f32 v[138:139], v[138:139], s[44:45], v[224:225] op_sel_hi:[1,0,1]
	v_pk_fma_f32 v[140:141], v[140:141], s[44:45], v[226:227] op_sel_hi:[1,0,1]
	v_pk_fma_f32 v[142:143], v[142:143], s[44:45], v[228:229] op_sel_hi:[1,0,1]
	v_pk_fma_f32 v[144:145], v[144:145], s[44:45], v[230:231] op_sel_hi:[1,0,1]
	v_pk_fma_f32 v[146:147], v[146:147], s[44:45], v[232:233] op_sel_hi:[1,0,1]
	s_branch .Latt_t1_ab_sm_a_fdone
.Latt_t1_ab_sm_a_cfma:
	v_pk_fma_f32 v[132:133], v[132:133], s[44:45], v[218:219] op_sel_hi:[1,0,0]
	v_pk_fma_f32 v[134:135], v[134:135], s[44:45], v[218:219] op_sel_hi:[1,0,0]
	v_pk_fma_f32 v[136:137], v[136:137], s[44:45], v[218:219] op_sel_hi:[1,0,0]
	v_pk_fma_f32 v[138:139], v[138:139], s[44:45], v[218:219] op_sel_hi:[1,0,0]
	v_pk_fma_f32 v[140:141], v[140:141], s[44:45], v[218:219] op_sel_hi:[1,0,0]
	v_pk_fma_f32 v[142:143], v[142:143], s[44:45], v[218:219] op_sel_hi:[1,0,0]
	v_pk_fma_f32 v[144:145], v[144:145], s[44:45], v[218:219] op_sel_hi:[1,0,0]
	v_pk_fma_f32 v[146:147], v[146:147], s[44:45], v[218:219] op_sel_hi:[1,0,0]
.Latt_t1_ab_sm_a_fdone:
	v_max3_f32 v1, v215, v132, v133
	v_max3_f32 v1, v1, v134, v135
	v_max3_f32 v1, v1, v136, v137
	v_max3_f32 v1, v1, v138, v139
	v_max3_f32 v1, v1, v140, v141
	v_max3_f32 v1, v1, v142, v143
	v_max3_f32 v1, v1, v144, v145
	v_max3_f32 v1, v1, v146, v147
	v_mov_b32_e32 v3, v1
	s_nop 1
	v_permlane16_swap_b32_e32 v3, v1
	v_max_f32_e32 v1, v1, v3
	v_mov_b32_e32 v3, v1
	s_nop 1
	v_permlane32_swap_b32_e32 v3, v1
	v_max_f32_e32 v217, v1, v3
	v_sub_f32_e32 v1, v215, v217
	v_exp_f32_e32 v2, v1
	v_mov_b32_e32 v180, v217
	v_cmp_neq_f32_e32 vcc, 1.0, v2
	s_cbranch_vccz .Latt_t1_ab_sm_a_norescale
	v_pk_mul_f32 v[112:113], v[112:113], v[2:3] op_sel_hi:[1,0]
	v_pk_mul_f32 v[114:115], v[114:115], v[2:3] op_sel_hi:[1,0]
	v_pk_mul_f32 v[104:105], v[104:105], v[2:3] op_sel_hi:[1,0]
	v_pk_mul_f32 v[106:107], v[106:107], v[2:3] op_sel_hi:[1,0]
	v_pk_mul_f32 v[96:97], v[96:97], v[2:3] op_sel_hi:[1,0]
	v_pk_mul_f32 v[98:99], v[98:99], v[2:3] op_sel_hi:[1,0]
	v_pk_mul_f32 v[88:89], v[88:89], v[2:3] op_sel_hi:[1,0]
	v_pk_mul_f32 v[90:91], v[90:91], v[2:3] op_sel_hi:[1,0]
	v_pk_mul_f32 v[80:81], v[80:81], v[2:3] op_sel_hi:[1,0]
	v_pk_mul_f32 v[82:83], v[82:83], v[2:3] op_sel_hi:[1,0]
	v_pk_mul_f32 v[64:65], v[64:65], v[2:3] op_sel_hi:[1,0]
	v_pk_mul_f32 v[66:67], v[66:67], v[2:3] op_sel_hi:[1,0]
	v_pk_mul_f32 v[52:53], v[52:53], v[2:3] op_sel_hi:[1,0]
	v_pk_mul_f32 v[54:55], v[54:55], v[2:3] op_sel_hi:[1,0]
	v_pk_mul_f32 v[40:41], v[40:41], v[2:3] op_sel_hi:[1,0]
	v_pk_mul_f32 v[42:43], v[42:43], v[2:3] op_sel_hi:[1,0]
.Latt_t1_ab_sm_a_norescale:
	v_pk_add_f32 v[132:133], v[132:133], v[180:181] op_sel_hi:[1,0] neg_lo:[0,1] neg_hi:[0,1]
	v_pk_add_f32 v[134:135], v[134:135], v[180:181] op_sel_hi:[1,0] neg_lo:[0,1] neg_hi:[0,1]
	v_pk_add_f32 v[136:137], v[136:137], v[180:181] op_sel_hi:[1,0] neg_lo:[0,1] neg_hi:[0,1]
	v_pk_add_f32 v[138:139], v[138:139], v[180:181] op_sel_hi:[1,0] neg_lo:[0,1] neg_hi:[0,1]
	v_pk_add_f32 v[140:141], v[140:141], v[180:181] op_sel_hi:[1,0] neg_lo:[0,1] neg_hi:[0,1]
	v_pk_add_f32 v[142:143], v[142:143], v[180:181] op_sel_hi:[1,0] neg_lo:[0,1] neg_hi:[0,1]
	v_pk_add_f32 v[144:145], v[144:145], v[180:181] op_sel_hi:[1,0] neg_lo:[0,1] neg_hi:[0,1]
	v_pk_add_f32 v[146:147], v[146:147], v[180:181] op_sel_hi:[1,0] neg_lo:[0,1] neg_hi:[0,1]
	v_exp_f32_e32 v132, v132
	v_exp_f32_e32 v133, v133
	v_exp_f32_e32 v134, v134
	v_add_f32_e32 v167, v132, v133
	v_exp_f32_e32 v135, v135
	v_add_f32_e32 v167, v134, v167
	v_exp_f32_e32 v136, v136
	v_add_f32_e32 v167, v135, v167
	v_exp_f32_e32 v137, v137
	v_add_f32_e32 v167, v136, v167
	v_exp_f32_e32 v138, v138
	v_add_f32_e32 v167, v137, v167
	v_exp_f32_e32 v139, v139
	v_add_f32_e32 v167, v138, v167
	v_exp_f32_e32 v140, v140
	v_add_f32_e32 v167, v139, v167
	v_exp_f32_e32 v141, v141
	v_add_f32_e32 v167, v140, v167
	v_exp_f32_e32 v142, v142
	v_add_f32_e32 v167, v141, v167
	v_exp_f32_e32 v143, v143
	v_add_f32_e32 v167, v142, v167
	v_exp_f32_e32 v144, v144
	v_add_f32_e32 v167, v143, v167
	v_exp_f32_e32 v145, v145
	v_add_f32_e32 v167, v144, v167
	v_exp_f32_e32 v146, v146
	v_add_f32_e32 v167, v145, v167
	v_exp_f32_e32 v147, v147
	v_add_f32_e32 v167, v146, v167
	s_nop 0
	v_add_f32_e32 v167, v147, v167
	v_fma_f32 v213, v213, v2, v167
	v_cvt_pk_bf16_f32 v132, v132, v133
	v_cvt_pk_bf16_f32 v133, v134, v135
	v_cvt_pk_bf16_f32 v134, v136, v137
	v_cvt_pk_bf16_f32 v135, v138, v139
	v_cvt_pk_bf16_f32 v136, v140, v141
	v_cvt_pk_bf16_f32 v137, v142, v143
	v_cvt_pk_bf16_f32 v138, v144, v145
	v_cvt_pk_bf16_f32 v139, v146, v147
	s_waitcnt lgkmcnt(0)
	s_cmp_gt_i32 s37, 5
	s_cbranch_scc0 .Latt_t1_ab_sm_b_cfma
	v_pk_fma_f32 v[148:149], v[148:149], s[44:45], v[234:235] op_sel_hi:[1,0,1]
	v_pk_fma_f32 v[150:151], v[150:151], s[44:45], v[236:237] op_sel_hi:[1,0,1]
	v_pk_fma_f32 v[152:153], v[152:153], s[44:45], v[238:239] op_sel_hi:[1,0,1]
	v_pk_fma_f32 v[154:155], v[154:155], s[44:45], v[240:241] op_sel_hi:[1,0,1]
	v_pk_fma_f32 v[156:157], v[156:157], s[44:45], v[242:243] op_sel_hi:[1,0,1]
	v_pk_fma_f32 v[158:159], v[158:159], s[44:45], v[244:245] op_sel_hi:[1,0,1]
	v_pk_fma_f32 v[160:161], v[160:161], s[44:45], v[246:247] op_sel_hi:[1,0,1]
	v_pk_fma_f32 v[162:163], v[162:163], s[44:45], v[248:249] op_sel_hi:[1,0,1]
	s_branch .Latt_t1_ab_sm_b_fdone
; __device__ __forceinline__ unsigned cvt_pk_bf16(float lo, float hi) { unsigned r; asm volatile("v_cvt_pk_bf16_f32 %0, %1, %2" : "=v"(r) : "v"(lo), "v"(hi)); return r; }
; __device__ __forceinline__ void attn_softmax(f32x4 (&sc)[4], float& m_run, float& l_run, f32x4 (&o)[8], const int j, const int tq, const int g, const LAS float* tb, bf16x8 (&pb)[2]) {
;     ...
;     mx = fmaxf(mx, __shfl_xor(mx, 16)); mx = fmaxf(mx, __shfl_xor(mx, 32));
;     const float alpha = __builtin_amdgcn_exp2f(m_run - mx); m_run = mx;
;     float ls = 0.f;
; #pragma unroll
;     for (int mt = 0; mt < 4; ++mt)
; #pragma unroll
;         for (int e = 0; e < 4; ++e) { sc[mt][e] = __builtin_amdgcn_exp2f(sc[mt][e] - mx); ls += sc[mt][e]; }
;     l_run = l_run * alpha + ls;
;     if (__builtin_amdgcn_ballot_w64(alpha != 1.0f) != 0ull) {
; #pragma unroll
;         for (int cc = 0; cc < 8; ++cc) o[cc] *= alpha;
;     }
; #pragma unroll
;     for (int s2 = 0; s2 < 2; ++s2) { u32x4 pw; pw.x = cvt_pk_bf16(sc[2 * s2][0], sc[2 * s2][1]); pw.y = cvt_pk_bf16(sc[2 * s2][2], sc[2 * s2][3]);
;         pw.z = cvt_pk_bf16(sc[2 * s2 + 1][0], sc[2 * s2 + 1][1]); pw.w = cvt_pk_bf16(sc[2 * s2 + 1][2], sc[2 * s2 + 1][3]); pb[s2] = __builtin_bit_cast(bf16x8, pw); }
.Latt_t1_ab_sm_b_cfma:
	v_pk_fma_f32 v[148:149], v[148:149], s[44:45], v[234:235] op_sel_hi:[1,0,0]
	v_pk_fma_f32 v[150:151], v[150:151], s[44:45], v[234:235] op_sel_hi:[1,0,0]
	v_pk_fma_f32 v[152:153], v[152:153], s[44:45], v[234:235] op_sel_hi:[1,0,0]
	v_pk_fma_f32 v[154:155], v[154:155], s[44:45], v[234:235] op_sel_hi:[1,0,0]
	v_pk_fma_f32 v[156:157], v[156:157], s[44:45], v[234:235] op_sel_hi:[1,0,0]
	v_pk_fma_f32 v[158:159], v[158:159], s[44:45], v[234:235] op_sel_hi:[1,0,0]
	v_pk_fma_f32 v[160:161], v[160:161], s[44:45], v[234:235] op_sel_hi:[1,0,0]
	v_pk_fma_f32 v[162:163], v[162:163], s[44:45], v[234:235] op_sel_hi:[1,0,0]
.Latt_t1_ab_sm_b_fdone:
	v_add_u32_e32 v172, v192, v193
	v_add_u32_e32 v173, v192, v195
	v_add_u32_e32 v174, v192, v197
	v_add_u32_e32 v175, v192, v199
	v_add_u32_e32 v176, v192, v201
	v_add_u32_e32 v177, v192, v203
	v_add_u32_e32 v178, v192, v205
	v_add_u32_e32 v179, v192, v207
	ds_read_b64_tr_b16 v[218:219], v172 offset:16384
	ds_read_b64_tr_b16 v[220:221], v172 offset:20480
	ds_read_b64_tr_b16 v[222:223], v173 offset:16384
	ds_read_b64_tr_b16 v[224:225], v173 offset:20480
	ds_read_b64_tr_b16 v[226:227], v174 offset:16384
	ds_read_b64_tr_b16 v[228:229], v174 offset:20480
	ds_read_b64_tr_b16 v[230:231], v175 offset:16384
	ds_read_b64_tr_b16 v[232:233], v175 offset:20480
	ds_read_b64_tr_b16 v[234:235], v176 offset:16384
	ds_read_b64_tr_b16 v[236:237], v176 offset:20480
	ds_read_b64_tr_b16 v[238:239], v177 offset:16384
	ds_read_b64_tr_b16 v[240:241], v177 offset:20480
	ds_read_b64_tr_b16 v[242:243], v178 offset:16384
	ds_read_b64_tr_b16 v[244:245], v178 offset:20480
	v_max3_f32 v1, v214, v148, v149
	v_max3_f32 v1, v1, v150, v151
	v_max3_f32 v1, v1, v152, v153
	v_max3_f32 v1, v1, v154, v155
	v_max3_f32 v1, v1, v156, v157
	v_max3_f32 v1, v1, v158, v159
	v_max3_f32 v1, v1, v160, v161
	v_max3_f32 v1, v1, v162, v163
	v_mov_b32_e32 v3, v1
	s_nop 1
	v_permlane16_swap_b32_e32 v3, v1
	v_max_f32_e32 v1, v1, v3
	v_mov_b32_e32 v3, v1
	s_nop 1
	v_permlane32_swap_b32_e32 v3, v1
	v_max_f32_e32 v216, v1, v3
	v_sub_f32_e32 v1, v214, v216
	v_exp_f32_e32 v2, v1
	v_mov_b32_e32 v180, v216
	v_cmp_neq_f32_e32 vcc, 1.0, v2
	s_cbranch_vccz .Latt_t1_ab_sm_b_norescale
	v_pk_mul_f32 v[108:109], v[108:109], v[2:3] op_sel_hi:[1,0]
	v_pk_mul_f32 v[110:111], v[110:111], v[2:3] op_sel_hi:[1,0]
	v_pk_mul_f32 v[100:101], v[100:101], v[2:3] op_sel_hi:[1,0]
	v_pk_mul_f32 v[102:103], v[102:103], v[2:3] op_sel_hi:[1,0]
	v_pk_mul_f32 v[92:93], v[92:93], v[2:3] op_sel_hi:[1,0]
	v_pk_mul_f32 v[94:95], v[94:95], v[2:3] op_sel_hi:[1,0]
	v_pk_mul_f32 v[84:85], v[84:85], v[2:3] op_sel_hi:[1,0]
	v_pk_mul_f32 v[86:87], v[86:87], v[2:3] op_sel_hi:[1,0]
	v_pk_mul_f32 v[76:77], v[76:77], v[2:3] op_sel_hi:[1,0]
	v_pk_mul_f32 v[78:79], v[78:79], v[2:3] op_sel_hi:[1,0]
	v_pk_mul_f32 v[60:61], v[60:61], v[2:3] op_sel_hi:[1,0]
	v_pk_mul_f32 v[62:63], v[62:63], v[2:3] op_sel_hi:[1,0]
	v_pk_mul_f32 v[48:49], v[48:49], v[2:3] op_sel_hi:[1,0]
	v_pk_mul_f32 v[50:51], v[50:51], v[2:3] op_sel_hi:[1,0]
	v_pk_mul_f32 v[36:37], v[36:37], v[2:3] op_sel_hi:[1,0]
	v_pk_mul_f32 v[38:39], v[38:39], v[2:3] op_sel_hi:[1,0]
.Latt_t1_ab_sm_b_norescale:
	v_pk_add_f32 v[148:149], v[148:149], v[180:181] op_sel_hi:[1,0] neg_lo:[0,1] neg_hi:[0,1]
	v_pk_add_f32 v[150:151], v[150:151], v[180:181] op_sel_hi:[1,0] neg_lo:[0,1] neg_hi:[0,1]
	v_pk_add_f32 v[152:153], v[152:153], v[180:181] op_sel_hi:[1,0] neg_lo:[0,1] neg_hi:[0,1]
	v_pk_add_f32 v[154:155], v[154:155], v[180:181] op_sel_hi:[1,0] neg_lo:[0,1] neg_hi:[0,1]
	v_pk_add_f32 v[156:157], v[156:157], v[180:181] op_sel_hi:[1,0] neg_lo:[0,1] neg_hi:[0,1]
	v_pk_add_f32 v[158:159], v[158:159], v[180:181] op_sel_hi:[1,0] neg_lo:[0,1] neg_hi:[0,1]
	v_pk_add_f32 v[160:161], v[160:161], v[180:181] op_sel_hi:[1,0] neg_lo:[0,1] neg_hi:[0,1]
	v_pk_add_f32 v[162:163], v[162:163], v[180:181] op_sel_hi:[1,0] neg_lo:[0,1] neg_hi:[0,1]
	v_exp_f32_e32 v148, v148
	v_exp_f32_e32 v149, v149
	v_exp_f32_e32 v150, v150
	v_add_f32_e32 v167, v148, v149
	v_exp_f32_e32 v151, v151
	v_add_f32_e32 v167, v150, v167
	v_exp_f32_e32 v152, v152
	v_add_f32_e32 v167, v151, v167
	v_exp_f32_e32 v153, v153
	v_add_f32_e32 v167, v152, v167
	v_exp_f32_e32 v154, v154
	v_add_f32_e32 v167, v153, v167
	v_exp_f32_e32 v155, v155
	v_add_f32_e32 v167, v154, v167
	v_exp_f32_e32 v156, v156
	v_add_f32_e32 v167, v155, v167
	v_exp_f32_e32 v157, v157
	v_add_f32_e32 v167, v156, v167
	v_exp_f32_e32 v158, v158
	v_add_f32_e32 v167, v157, v167
	v_exp_f32_e32 v159, v159
	v_add_f32_e32 v167, v158, v167
	v_exp_f32_e32 v160, v160
	v_add_f32_e32 v167, v159, v167
	v_exp_f32_e32 v161, v161
	v_add_f32_e32 v167, v160, v167
	v_exp_f32_e32 v162, v162
	v_add_f32_e32 v167, v161, v167
	v_exp_f32_e32 v163, v163
	v_add_f32_e32 v167, v162, v167
	s_nop 0
	v_add_f32_e32 v167, v163, v167
	v_fma_f32 v212, v212, v2, v167
	v_cvt_pk_bf16_f32 v148, v148, v149
	v_cvt_pk_bf16_f32 v149, v150, v151
	v_cvt_pk_bf16_f32 v150, v152, v153
	v_cvt_pk_bf16_f32 v151, v154, v155
	v_cvt_pk_bf16_f32 v152, v156, v157
	v_cvt_pk_bf16_f32 v153, v158, v159
	v_cvt_pk_bf16_f32 v154, v160, v161
	v_cvt_pk_bf16_f32 v155, v162, v163
	s_waitcnt lgkmcnt(12)
	v_mfma_f32_16x16x32_bf16 v[112:115], v[218:221], v[132:135], v[112:115]
	v_mfma_f32_16x16x32_bf16 v[108:111], v[218:221], v[148:151], v[108:111]
	ds_read_b64_tr_b16 v[218:219], v179 offset:16384
	ds_read_b64_tr_b16 v[220:221], v179 offset:20480
	s_waitcnt lgkmcnt(12)
	v_mfma_f32_16x16x32_bf16 v[104:107], v[222:225], v[132:135], v[104:107]
	v_mfma_f32_16x16x32_bf16 v[100:103], v[222:225], v[148:151], v[100:103]
	ds_read_b64_tr_b16 v[222:223], v172 offset:24576
	ds_read_b64_tr_b16 v[224:225], v172 offset:28672
	s_waitcnt lgkmcnt(12)
	v_mfma_f32_16x16x32_bf16 v[96:99], v[226:229], v[132:135], v[96:99]
	v_mfma_f32_16x16x32_bf16 v[92:95], v[226:229], v[148:151], v[92:95]
	ds_read_b64_tr_b16 v[226:227], v173 offset:24576
	ds_read_b64_tr_b16 v[228:229], v173 offset:28672
	s_waitcnt lgkmcnt(12)
	v_mfma_f32_16x16x32_bf16 v[88:91], v[230:233], v[132:135], v[88:91]
	v_mfma_f32_16x16x32_bf16 v[84:87], v[230:233], v[148:151], v[84:87]
	ds_read_b64_tr_b16 v[230:231], v174 offset:24576
	ds_read_b64_tr_b16 v[232:233], v174 offset:28672
	s_waitcnt lgkmcnt(12)
	v_mfma_f32_16x16x32_bf16 v[80:83], v[234:237], v[132:135], v[80:83]
	v_mfma_f32_16x16x32_bf16 v[76:79], v[234:237], v[148:151], v[76:79]
	ds_read_b64_tr_b16 v[234:235], v175 offset:24576
	ds_read_b64_tr_b16 v[236:237], v175 offset:28672
	s_waitcnt lgkmcnt(12)
	v_mfma_f32_16x16x32_bf16 v[64:67], v[238:241], v[132:135], v[64:67]
	v_mfma_f32_16x16x32_bf16 v[60:63], v[238:241], v[148:151], v[60:63]
	ds_read_b64_tr_b16 v[238:239], v176 offset:24576
	ds_read_b64_tr_b16 v[240:241], v176 offset:28672
	s_waitcnt lgkmcnt(12)
	v_mfma_f32_16x16x32_bf16 v[52:55], v[242:245], v[132:135], v[52:55]
	v_mfma_f32_16x16x32_bf16 v[48:51], v[242:245], v[148:151], v[48:51]
	ds_read_b64_tr_b16 v[242:243], v177 offset:24576
	ds_read_b64_tr_b16 v[244:245], v177 offset:28672
	s_waitcnt lgkmcnt(12)
	v_mfma_f32_16x16x32_bf16 v[40:43], v[218:221], v[132:135], v[40:43]
	v_mfma_f32_16x16x32_bf16 v[36:39], v[218:221], v[148:151], v[36:39]
	ds_read_b64_tr_b16 v[218:219], v178 offset:24576
	ds_read_b64_tr_b16 v[220:221], v178 offset:28672
	s_waitcnt lgkmcnt(12)
	v_mfma_f32_16x16x32_bf16 v[112:115], v[222:225], v[136:139], v[112:115]
	v_mfma_f32_16x16x32_bf16 v[108:111], v[222:225], v[152:155], v[108:111]
	ds_read_b64_tr_b16 v[222:223], v179 offset:24576
	ds_read_b64_tr_b16 v[224:225], v179 offset:28672
	s_waitcnt lgkmcnt(12)
	v_mfma_f32_16x16x32_bf16 v[104:107], v[226:229], v[136:139], v[104:107]
	v_mfma_f32_16x16x32_bf16 v[100:103], v[226:229], v[152:155], v[100:103]
	s_waitcnt lgkmcnt(10)
	v_mfma_f32_16x16x32_bf16 v[96:99], v[230:233], v[136:139], v[96:99]
	v_mfma_f32_16x16x32_bf16 v[92:95], v[230:233], v[152:155], v[92:95]
	s_waitcnt lgkmcnt(8)
	v_mfma_f32_16x16x32_bf16 v[88:91], v[234:237], v[136:139], v[88:91]
	v_mfma_f32_16x16x32_bf16 v[84:87], v[234:237], v[152:155], v[84:87]
	s_waitcnt lgkmcnt(6)
	v_mfma_f32_16x16x32_bf16 v[80:83], v[238:241], v[136:139], v[80:83]
	v_mfma_f32_16x16x32_bf16 v[76:79], v[238:241], v[152:155], v[76:79]
	s_waitcnt lgkmcnt(4)
	v_mfma_f32_16x16x32_bf16 v[64:67], v[242:245], v[136:139], v[64:67]
	v_mfma_f32_16x16x32_bf16 v[60:63], v[242:245], v[152:155], v[60:63]
	s_waitcnt lgkmcnt(2)
	v_mfma_f32_16x16x32_bf16 v[52:55], v[218:221], v[136:139], v[52:55]
	v_mfma_f32_16x16x32_bf16 v[48:51], v[218:221], v[152:155], v[48:51]
	s_waitcnt lgkmcnt(0)
	v_mfma_f32_16x16x32_bf16 v[40:43], v[222:225], v[136:139], v[40:43]
	v_mfma_f32_16x16x32_bf16 v[36:39], v[222:225], v[152:155], v[36:39]
	s_branch .LBB0_365
.Latt_t1_a:
	s_sub_i32 s36, s74, s93
	s_add_i32 s37, s36, -1
	v_add_u32_e32 v164, v187, v189
	v_add_u32_e32 v165, v187, v190
	v_add_u32_e32 v166, v187, v191
	ds_read_b128 v[218:221], v211
	ds_read_b128 v[222:225], v164
	ds_read_b128 v[226:229], v165
	ds_read_b128 v[230:233], v166
	ds_read_b128 v[234:237], v211 offset:4096
	ds_read_b128 v[238:241], v164 offset:4096
	ds_read_b128 v[242:245], v165 offset:4096
	ds_read_b128 v[246:249], v166 offset:4096
	s_waitcnt lgkmcnt(7)
	v_mfma_f32_16x16x32_bf16 v[132:135], v[218:221], v[4:7], 0
	ds_read_b128 v[218:221], v211 offset:8192
	s_waitcnt lgkmcnt(7)
	v_mfma_f32_16x16x32_bf16 v[132:135], v[222:225], v[12:15], v[132:135]
	ds_read_b128 v[222:225], v164 offset:8192
	s_waitcnt lgkmcnt(7)
	v_mfma_f32_16x16x32_bf16 v[132:135], v[226:229], v[20:23], v[132:135]
	ds_read_b128 v[226:229], v165 offset:8192
	s_waitcnt lgkmcnt(7)
	v_mfma_f32_16x16x32_bf16 v[132:135], v[230:233], v[28:31], v[132:135]
	ds_read_b128 v[230:233], v166 offset:8192
	s_waitcnt lgkmcnt(7)
	v_mfma_f32_16x16x32_bf16 v[136:139], v[234:237], v[4:7], 0
	ds_read_b128 v[234:237], v211 offset:12288
	s_waitcnt lgkmcnt(7)
	v_mfma_f32_16x16x32_bf16 v[136:139], v[238:241], v[12:15], v[136:139]
	ds_read_b128 v[238:241], v164 offset:12288
	s_waitcnt lgkmcnt(7)
	v_mfma_f32_16x16x32_bf16 v[136:139], v[242:245], v[20:23], v[136:139]
	ds_read_b128 v[242:245], v165 offset:12288
	s_waitcnt lgkmcnt(7)
	v_mfma_f32_16x16x32_bf16 v[136:139], v[246:249], v[28:31], v[136:139]
	ds_read_b128 v[246:249], v166 offset:12288
	s_waitcnt lgkmcnt(7)
	v_mfma_f32_16x16x32_bf16 v[140:143], v[218:221], v[4:7], 0
	s_waitcnt lgkmcnt(6)
	v_mfma_f32_16x16x32_bf16 v[140:143], v[222:225], v[12:15], v[140:143]
	s_waitcnt lgkmcnt(5)
	v_mfma_f32_16x16x32_bf16 v[140:143], v[226:229], v[20:23], v[140:143]
	s_waitcnt lgkmcnt(4)
	v_mfma_f32_16x16x32_bf16 v[140:143], v[230:233], v[28:31], v[140:143]
	s_waitcnt lgkmcnt(0)
	s_cmp_gt_i32 s36, 5
	s_cbranch_scc0 .Latt_t1_a_bc_a_const
	s_mov_b32 s38, 0x10100
	v_lshl_add_u32 v1, v210, 2, s38
	v_min_i32_e32 v218, 0x10400, v1
	v_add_u32_e32 v219, 0xfffffffc, v1
	v_min_i32_e32 v219, 0x10400, v219
	v_add_u32_e32 v220, 0xfffffff8, v1
	v_min_i32_e32 v220, 0x10400, v220
	v_add_u32_e32 v221, 0xfffffff4, v1
	v_min_i32_e32 v221, 0x10400, v221
	v_add_u32_e32 v222, 0xffffffc0, v1
	v_min_i32_e32 v222, 0x10400, v222
	v_add_u32_e32 v223, 0xffffffbc, v1
	v_min_i32_e32 v223, 0x10400, v223
	v_add_u32_e32 v224, 0xffffffb8, v1
	v_min_i32_e32 v224, 0x10400, v224
	v_add_u32_e32 v225, 0xffffffb4, v1
	v_min_i32_e32 v225, 0x10400, v225
	v_add_u32_e32 v226, 0xffffff80, v1
	v_min_i32_e32 v226, 0x10400, v226
	v_add_u32_e32 v227, 0xffffff7c, v1
	v_min_i32_e32 v227, 0x10400, v227
	v_add_u32_e32 v228, 0xffffff78, v1
	v_min_i32_e32 v228, 0x10400, v228
	v_add_u32_e32 v229, 0xffffff74, v1
	v_min_i32_e32 v229, 0x10400, v229
	v_add_u32_e32 v230, 0xffffff40, v1
	v_min_i32_e32 v230, 0x10400, v230
	v_add_u32_e32 v231, 0xffffff3c, v1
	v_min_i32_e32 v231, 0x10400, v231
	v_add_u32_e32 v232, 0xffffff38, v1
	v_min_i32_e32 v232, 0x10400, v232
	v_add_u32_e32 v233, 0xffffff34, v1
	v_min_i32_e32 v233, 0x10400, v233
	ds_read_b32 v218, v218
	ds_read_b32 v219, v219
	ds_read_b32 v220, v220
	ds_read_b32 v221, v221
	ds_read_b32 v222, v222
	ds_read_b32 v223, v223
	ds_read_b32 v224, v224
	ds_read_b32 v225, v225
	ds_read_b32 v226, v226
	ds_read_b32 v227, v227
	ds_read_b32 v228, v228
	ds_read_b32 v229, v229
	ds_read_b32 v230, v230
	ds_read_b32 v231, v231
	ds_read_b32 v232, v232
	ds_read_b32 v233, v233
	s_branch .Latt_t1_a_bc_a_done

; __device__ __forceinline__ void attn_softmax(f32x4 (&sc)[4], float& m_run, float& l_run, f32x4 (&o)[8], const int j, const int tq, const int g, const LAS float* tb, bf16x8 (&pb)[2]) {
;     ...
;     if (j <= 5) { const float bc = tb[256];
; #pragma unroll
;         for (int mt = 0; mt < 4; ++mt)
; #pragma unroll
;             for (int e = 0; e < 4; ++e) { sc[mt][e] = sc[mt][e] * SC + bc; mx = fmaxf(mx, sc[mt][e]); } }
;     else { const int relb = tq + 64 * (8 - j) - 4 * g;
; #pragma unroll
;         for (int mt = 0; mt < 4; ++mt)
; #pragma unroll
;             for (int e = 0; e < 4; ++e) { int rel = relb - 16 * mt - e; rel = rel > 128 ? 128 : rel; sc[mt][e] = sc[mt][e] * SC + tb[rel + 128]; mx = fmaxf(mx, sc[mt][e]); } }
.Latt_t1_a_bc_a_done:
	v_mfma_f32_16x16x32_bf16 v[144:147], v[234:237], v[4:7], 0
	v_mfma_f32_16x16x32_bf16 v[144:147], v[238:241], v[12:15], v[144:147]
	v_mfma_f32_16x16x32_bf16 v[144:147], v[242:245], v[20:23], v[144:147]
	v_mfma_f32_16x16x32_bf16 v[144:147], v[246:249], v[28:31], v[144:147]
	s_waitcnt lgkmcnt(0)
	s_nop 7
	s_cmp_gt_i32 s36, 5
	s_cbranch_scc0 .Latt_t1_a_sm_a_cfma
	v_pk_fma_f32 v[132:133], v[132:133], s[44:45], v[218:219] op_sel_hi:[1,0,1]
	v_pk_fma_f32 v[134:135], v[134:135], s[44:45], v[220:221] op_sel_hi:[1,0,1]
	v_pk_fma_f32 v[136:137], v[136:137], s[44:45], v[222:223] op_sel_hi:[1,0,1]
	v_pk_fma_f32 v[138:139], v[138:139], s[44:45], v[224:225] op_sel_hi:[1,0,1]
	v_pk_fma_f32 v[140:141], v[140:141], s[44:45], v[226:227] op_sel_hi:[1,0,1]
	v_pk_fma_f32 v[142:143], v[142:143], s[44:45], v[228:229] op_sel_hi:[1,0,1]
	v_pk_fma_f32 v[144:145], v[144:145], s[44:45], v[230:231] op_sel_hi:[1,0,1]
	v_pk_fma_f32 v[146:147], v[146:147], s[44:45], v[232:233] op_sel_hi:[1,0,1]
	s_branch .Latt_t1_a_sm_a_fdone

; __device__ __forceinline__ unsigned cvt_pk_bf16(float lo, float hi) { unsigned r; asm volatile("v_cvt_pk_bf16_f32 %0, %1, %2" : "=v"(r) : "v"(lo), "v"(hi)); return r; }
; __device__ __forceinline__ void attn_softmax(f32x4 (&sc)[4], float& m_run, float& l_run, f32x4 (&o)[8], const int j, const int tq, const int g, const LAS float* tb, bf16x8 (&pb)[2]) {
;     ...
;     mx = fmaxf(mx, __shfl_xor(mx, 16)); mx = fmaxf(mx, __shfl_xor(mx, 32));
;     const float alpha = __builtin_amdgcn_exp2f(m_run - mx); m_run = mx;
;     float ls = 0.f;
; #pragma unroll
;     for (int mt = 0; mt < 4; ++mt)
; #pragma unroll
;         for (int e = 0; e < 4; ++e) { sc[mt][e] = __builtin_amdgcn_exp2f(sc[mt][e] - mx); ls += sc[mt][e]; }
;     l_run = l_run * alpha + ls;
;     if (__builtin_amdgcn_ballot_w64(alpha != 1.0f) != 0ull) {
; #pragma unroll
;         for (int cc = 0; cc < 8; ++cc) o[cc] *= alpha;
;     }
; #pragma unroll
;     for (int s2 = 0; s2 < 2; ++s2) { u32x4 pw; pw.x = cvt_pk_bf16(sc[2 * s2][0], sc[2 * s2][1]); pw.y = cvt_pk_bf16(sc[2 * s2][2], sc[2 * s2][3]);
;         pw.z = cvt_pk_bf16(sc[2 * s2 + 1][0], sc[2 * s2 + 1][1]); pw.w = cvt_pk_bf16(sc[2 * s2 + 1][2], sc[2 * s2 + 1][3]); pb[s2] = __builtin_bit_cast(bf16x8, pw); }
.Latt_t1_a_sm_a_fdone:
	v_add_u32_e32 v172, v192, v193
	v_add_u32_e32 v173, v192, v195
	v_add_u32_e32 v174, v192, v197
	v_add_u32_e32 v175, v192, v199
	v_add_u32_e32 v176, v192, v201
	v_add_u32_e32 v177, v192, v203
	v_add_u32_e32 v178, v192, v205
	v_add_u32_e32 v179, v192, v207
	ds_read_b64_tr_b16 v[218:219], v172 offset:16384
	ds_read_b64_tr_b16 v[220:221], v172 offset:20480
	ds_read_b64_tr_b16 v[222:223], v173 offset:16384
	ds_read_b64_tr_b16 v[224:225], v173 offset:20480
	ds_read_b64_tr_b16 v[226:227], v174 offset:16384
	ds_read_b64_tr_b16 v[228:229], v174 offset:20480
	ds_read_b64_tr_b16 v[230:231], v175 offset:16384
	ds_read_b64_tr_b16 v[232:233], v175 offset:20480
	ds_read_b64_tr_b16 v[234:235], v176 offset:16384
	ds_read_b64_tr_b16 v[236:237], v176 offset:20480
	ds_read_b64_tr_b16 v[238:239], v177 offset:16384
	ds_read_b64_tr_b16 v[240:241], v177 offset:20480
	ds_read_b64_tr_b16 v[242:243], v178 offset:16384
	ds_read_b64_tr_b16 v[244:245], v178 offset:20480
	v_max3_f32 v1, v215, v132, v133
	v_max3_f32 v1, v1, v134, v135
	v_max3_f32 v1, v1, v136, v137
	v_max3_f32 v1, v1, v138, v139
	v_max3_f32 v1, v1, v140, v141
	v_max3_f32 v1, v1, v142, v143
	v_max3_f32 v1, v1, v144, v145
	v_max3_f32 v1, v1, v146, v147
	v_mov_b32_e32 v3, v1
	s_nop 1
	v_permlane16_swap_b32_e32 v3, v1
	v_max_f32_e32 v1, v1, v3
	v_mov_b32_e32 v3, v1
	s_nop 1
	v_permlane32_swap_b32_e32 v3, v1
	v_max_f32_e32 v217, v1, v3
	v_sub_f32_e32 v1, v215, v217
	v_exp_f32_e32 v2, v1
	v_mov_b32_e32 v180, v217
	v_cmp_neq_f32_e32 vcc, 1.0, v2
	s_cbranch_vccz .Latt_t1_a_sm_a_norescale
	v_pk_mul_f32 v[112:113], v[112:113], v[2:3] op_sel_hi:[1,0]
	v_pk_mul_f32 v[114:115], v[114:115], v[2:3] op_sel_hi:[1,0]
	v_pk_mul_f32 v[104:105], v[104:105], v[2:3] op_sel_hi:[1,0]
	v_pk_mul_f32 v[106:107], v[106:107], v[2:3] op_sel_hi:[1,0]
	v_pk_mul_f32 v[96:97], v[96:97], v[2:3] op_sel_hi:[1,0]
	v_pk_mul_f32 v[98:99], v[98:99], v[2:3] op_sel_hi:[1,0]
	v_pk_mul_f32 v[88:89], v[88:89], v[2:3] op_sel_hi:[1,0]
	v_pk_mul_f32 v[90:91], v[90:91], v[2:3] op_sel_hi:[1,0]
	v_pk_mul_f32 v[80:81], v[80:81], v[2:3] op_sel_hi:[1,0]
	v_pk_mul_f32 v[82:83], v[82:83], v[2:3] op_sel_hi:[1,0]
	v_pk_mul_f32 v[64:65], v[64:65], v[2:3] op_sel_hi:[1,0]
	v_pk_mul_f32 v[66:67], v[66:67], v[2:3] op_sel_hi:[1,0]
	v_pk_mul_f32 v[52:53], v[52:53], v[2:3] op_sel_hi:[1,0]
	v_pk_mul_f32 v[54:55], v[54:55], v[2:3] op_sel_hi:[1,0]
	v_pk_mul_f32 v[40:41], v[40:41], v[2:3] op_sel_hi:[1,0]
	v_pk_mul_f32 v[42:43], v[42:43], v[2:3] op_sel_hi:[1,0]
.Latt_t1_a_sm_a_norescale:
	v_pk_add_f32 v[132:133], v[132:133], v[180:181] op_sel_hi:[1,0] neg_lo:[0,1] neg_hi:[0,1]
	v_pk_add_f32 v[134:135], v[134:135], v[180:181] op_sel_hi:[1,0] neg_lo:[0,1] neg_hi:[0,1]
	v_pk_add_f32 v[136:137], v[136:137], v[180:181] op_sel_hi:[1,0] neg_lo:[0,1] neg_hi:[0,1]
	v_pk_add_f32 v[138:139], v[138:139], v[180:181] op_sel_hi:[1,0] neg_lo:[0,1] neg_hi:[0,1]
	v_pk_add_f32 v[140:141], v[140:141], v[180:181] op_sel_hi:[1,0] neg_lo:[0,1] neg_hi:[0,1]
	v_pk_add_f32 v[142:143], v[142:143], v[180:181] op_sel_hi:[1,0] neg_lo:[0,1] neg_hi:[0,1]
	v_pk_add_f32 v[144:145], v[144:145], v[180:181] op_sel_hi:[1,0] neg_lo:[0,1] neg_hi:[0,1]
	v_pk_add_f32 v[146:147], v[146:147], v[180:181] op_sel_hi:[1,0] neg_lo:[0,1] neg_hi:[0,1]
	v_exp_f32_e32 v132, v132
	v_exp_f32_e32 v133, v133
	v_exp_f32_e32 v134, v134
	v_add_f32_e32 v167, v132, v133
	v_exp_f32_e32 v135, v135
	v_add_f32_e32 v167, v134, v167
	v_exp_f32_e32 v136, v136
	v_add_f32_e32 v167, v135, v167
	v_exp_f32_e32 v137, v137
	v_add_f32_e32 v167, v136, v167
	v_exp_f32_e32 v138, v138
	v_add_f32_e32 v167, v137, v167
	v_exp_f32_e32 v139, v139
	v_add_f32_e32 v167, v138, v167
	v_exp_f32_e32 v140, v140
	v_add_f32_e32 v167, v139, v167
	v_exp_f32_e32 v141, v141
	v_add_f32_e32 v167, v140, v167
	v_exp_f32_e32 v142, v142
	v_add_f32_e32 v167, v141, v167
	v_exp_f32_e32 v143, v143
	v_add_f32_e32 v167, v142, v167
	v_exp_f32_e32 v144, v144
	v_add_f32_e32 v167, v143, v167
	v_exp_f32_e32 v145, v145
	v_add_f32_e32 v167, v144, v167
	v_exp_f32_e32 v146, v146
	v_add_f32_e32 v167, v145, v167
	v_exp_f32_e32 v147, v147
	v_add_f32_e32 v167, v146, v167
	s_nop 0
	v_add_f32_e32 v167, v147, v167
	v_fma_f32 v213, v213, v2, v167
	v_cvt_pk_bf16_f32 v132, v132, v133
	v_cvt_pk_bf16_f32 v133, v134, v135
	v_cvt_pk_bf16_f32 v134, v136, v137
	v_cvt_pk_bf16_f32 v135, v138, v139
	v_cvt_pk_bf16_f32 v136, v140, v141
	v_cvt_pk_bf16_f32 v137, v142, v143
	v_cvt_pk_bf16_f32 v138, v144, v145
	v_cvt_pk_bf16_f32 v139, v146, v147
	s_waitcnt lgkmcnt(12)
	v_mfma_f32_16x16x32_bf16 v[112:115], v[218:221], v[132:135], v[112:115]
	ds_read_b64_tr_b16 v[218:219], v179 offset:16384
	ds_read_b64_tr_b16 v[220:221], v179 offset:20480
	s_waitcnt lgkmcnt(12)
	v_mfma_f32_16x16x32_bf16 v[104:107], v[222:225], v[132:135], v[104:107]
	ds_read_b64_tr_b16 v[222:223], v172 offset:24576
	ds_read_b64_tr_b16 v[224:225], v172 offset:28672
	s_waitcnt lgkmcnt(12)
	v_mfma_f32_16x16x32_bf16 v[96:99], v[226:229], v[132:135], v[96:99]
	ds_read_b64_tr_b16 v[226:227], v173 offset:24576
	ds_read_b64_tr_b16 v[228:229], v173 offset:28672
	s_waitcnt lgkmcnt(12)
	v_mfma_f32_16x16x32_bf16 v[88:91], v[230:233], v[132:135], v[88:91]
	ds_read_b64_tr_b16 v[230:231], v174 offset:24576
	ds_read_b64_tr_b16 v[232:233], v174 offset:28672
	s_waitcnt lgkmcnt(12)
	v_mfma_f32_16x16x32_bf16 v[80:83], v[234:237], v[132:135], v[80:83]
	ds_read_b64_tr_b16 v[234:235], v175 offset:24576
	ds_read_b64_tr_b16 v[236:237], v175 offset:28672
	s_waitcnt lgkmcnt(12)
	v_mfma_f32_16x16x32_bf16 v[64:67], v[238:241], v[132:135], v[64:67]
	ds_read_b64_tr_b16 v[238:239], v176 offset:24576
	ds_read_b64_tr_b16 v[240:241], v176 offset:28672
	s_waitcnt lgkmcnt(12)
	v_mfma_f32_16x16x32_bf16 v[52:55], v[242:245], v[132:135], v[52:55]
	ds_read_b64_tr_b16 v[242:243], v177 offset:24576
	ds_read_b64_tr_b16 v[244:245], v177 offset:28672
	s_waitcnt lgkmcnt(12)
	v_mfma_f32_16x16x32_bf16 v[40:43], v[218:221], v[132:135], v[40:43]
	ds_read_b64_tr_b16 v[218:219], v178 offset:24576
	ds_read_b64_tr_b16 v[220:221], v178 offset:28672
	s_waitcnt lgkmcnt(12)
	v_mfma_f32_16x16x32_bf16 v[112:115], v[222:225], v[136:139], v[112:115]
	ds_read_b64_tr_b16 v[222:223], v179 offset:24576
	ds_read_b64_tr_b16 v[224:225], v179 offset:28672
	s_waitcnt lgkmcnt(12)
	v_mfma_f32_16x16x32_bf16 v[104:107], v[226:229], v[136:139], v[104:107]
	s_waitcnt lgkmcnt(10)
	v_mfma_f32_16x16x32_bf16 v[96:99], v[230:233], v[136:139], v[96:99]
	s_waitcnt lgkmcnt(8)
	v_mfma_f32_16x16x32_bf16 v[88:91], v[234:237], v[136:139], v[88:91]
	s_waitcnt lgkmcnt(6)
	v_mfma_f32_16x16x32_bf16 v[80:83], v[238:241], v[136:139], v[80:83]
	s_waitcnt lgkmcnt(4)
	v_mfma_f32_16x16x32_bf16 v[64:67], v[242:245], v[136:139], v[64:67]
	s_waitcnt lgkmcnt(2)
	v_mfma_f32_16x16x32_bf16 v[52:55], v[218:221], v[136:139], v[52:55]
	s_waitcnt lgkmcnt(0)
	v_mfma_f32_16x16x32_bf16 v[40:43], v[222:225], v[136:139], v[40:43]
	v_mov_b32_e32 v216, v214
	s_branch .LBB0_365
; __device__ __forceinline__ void attn_softmax(f32x4 (&sc)[4], float& m_run, float& l_run, f32x4 (&o)[8], const int j, const int tq, const int g, const LAS float* tb, bf16x8 (&pb)[2]) {
;     ...
;     else { const int relb = tq + 64 * (8 - j) - 4 * g;
; #pragma unroll
;         for (int mt = 0; mt < 4; ++mt)
; #pragma unroll
;             for (int e = 0; e < 4; ++e) { int rel = relb - 16 * mt - e; rel = rel > 128 ? 128 : rel; sc[mt][e] = sc[mt][e] * SC + tb[rel + 128]; mx = fmaxf(mx, sc[mt][e]); } }
.Latt_t1_b:
	s_sub_i32 s36, s74, s93
	s_add_i32 s37, s36, -1
	v_add_u32_e32 v164, v187, v189
	v_add_u32_e32 v165, v187, v190
	v_add_u32_e32 v166, v187, v191
	ds_read_b128 v[218:221], v211
	ds_read_b128 v[222:225], v164
	ds_read_b128 v[226:229], v165
	ds_read_b128 v[230:233], v166
	ds_read_b128 v[234:237], v211 offset:4096
	ds_read_b128 v[238:241], v164 offset:4096
	ds_read_b128 v[242:245], v165 offset:4096
	ds_read_b128 v[246:249], v166 offset:4096
	s_waitcnt lgkmcnt(7)
	v_mfma_f32_16x16x32_bf16 v[148:151], v[218:221], v[8:11], 0
	ds_read_b128 v[218:221], v211 offset:8192
	s_waitcnt lgkmcnt(7)
	v_mfma_f32_16x16x32_bf16 v[148:151], v[222:225], v[16:19], v[148:151]
	ds_read_b128 v[222:225], v164 offset:8192
	s_waitcnt lgkmcnt(7)
	v_mfma_f32_16x16x32_bf16 v[148:151], v[226:229], v[24:27], v[148:151]
	ds_read_b128 v[226:229], v165 offset:8192
	s_waitcnt lgkmcnt(7)
	v_mfma_f32_16x16x32_bf16 v[148:151], v[230:233], v[32:35], v[148:151]
	ds_read_b128 v[230:233], v166 offset:8192
	s_waitcnt lgkmcnt(7)
	v_mfma_f32_16x16x32_bf16 v[152:155], v[234:237], v[8:11], 0
	ds_read_b128 v[234:237], v211 offset:12288
	s_waitcnt lgkmcnt(7)
	v_mfma_f32_16x16x32_bf16 v[152:155], v[238:241], v[16:19], v[152:155]
	ds_read_b128 v[238:241], v164 offset:12288
	s_waitcnt lgkmcnt(7)
	v_mfma_f32_16x16x32_bf16 v[152:155], v[242:245], v[24:27], v[152:155]
	ds_read_b128 v[242:245], v165 offset:12288
	s_waitcnt lgkmcnt(7)
	v_mfma_f32_16x16x32_bf16 v[152:155], v[246:249], v[32:35], v[152:155]
	ds_read_b128 v[246:249], v166 offset:12288
	s_waitcnt lgkmcnt(7)
	v_mfma_f32_16x16x32_bf16 v[156:159], v[218:221], v[8:11], 0
	s_waitcnt lgkmcnt(6)
	v_mfma_f32_16x16x32_bf16 v[156:159], v[222:225], v[16:19], v[156:159]
	s_waitcnt lgkmcnt(5)
	v_mfma_f32_16x16x32_bf16 v[156:159], v[226:229], v[24:27], v[156:159]
	s_waitcnt lgkmcnt(4)
	v_mfma_f32_16x16x32_bf16 v[156:159], v[230:233], v[32:35], v[156:159]
	s_waitcnt lgkmcnt(0)
	s_cmp_gt_i32 s37, 5
	s_cbranch_scc0 .Latt_t1_b_bc_b_const
	s_mov_b32 s38, 0x10200
	v_lshl_add_u32 v1, v210, 2, s38
	v_min_i32_e32 v218, 0x10400, v1
	v_add_u32_e32 v219, 0xfffffffc, v1
	v_min_i32_e32 v219, 0x10400, v219
	v_add_u32_e32 v220, 0xfffffff8, v1
	v_min_i32_e32 v220, 0x10400, v220
	v_add_u32_e32 v221, 0xfffffff4, v1
	v_min_i32_e32 v221, 0x10400, v221
	v_add_u32_e32 v222, 0xffffffc0, v1
	v_min_i32_e32 v222, 0x10400, v222
	v_add_u32_e32 v223, 0xffffffbc, v1
	v_min_i32_e32 v223, 0x10400, v223
	v_add_u32_e32 v224, 0xffffffb8, v1
	v_min_i32_e32 v224, 0x10400, v224
	v_add_u32_e32 v225, 0xffffffb4, v1
	v_min_i32_e32 v225, 0x10400, v225
	v_add_u32_e32 v226, 0xffffff80, v1
	v_min_i32_e32 v226, 0x10400, v226
	v_add_u32_e32 v227, 0xffffff7c, v1
	v_min_i32_e32 v227, 0x10400, v227
	v_add_u32_e32 v228, 0xffffff78, v1
	v_min_i32_e32 v228, 0x10400, v228
	v_add_u32_e32 v229, 0xffffff74, v1
	v_min_i32_e32 v229, 0x10400, v229
	v_add_u32_e32 v230, 0xffffff40, v1
	v_min_i32_e32 v230, 0x10400, v230
	v_add_u32_e32 v231, 0xffffff3c, v1
	v_min_i32_e32 v231, 0x10400, v231
	v_add_u32_e32 v232, 0xffffff38, v1
	v_min_i32_e32 v232, 0x10400, v232
	v_add_u32_e32 v233, 0xffffff34, v1
	v_min_i32_e32 v233, 0x10400, v233
	ds_read_b32 v218, v218
	ds_read_b32 v219, v219
	ds_read_b32 v220, v220
	ds_read_b32 v221, v221
	ds_read_b32 v222, v222
	ds_read_b32 v223, v223
	ds_read_b32 v224, v224
	ds_read_b32 v225, v225
	ds_read_b32 v226, v226
	ds_read_b32 v227, v227
	ds_read_b32 v228, v228
	ds_read_b32 v229, v229
	ds_read_b32 v230, v230
	ds_read_b32 v231, v231
	ds_read_b32 v232, v232
	ds_read_b32 v233, v233
	s_branch .Latt_t1_b_bc_b_done

; __device__ __forceinline__ void attn_softmax(f32x4 (&sc)[4], float& m_run, float& l_run, f32x4 (&o)[8], const int j, const int tq, const int g, const LAS float* tb, bf16x8 (&pb)[2]) {
;     ...
;     if (j <= 5) { const float bc = tb[256];
; #pragma unroll
;         for (int mt = 0; mt < 4; ++mt)
; #pragma unroll
;             for (int e = 0; e < 4; ++e) { sc[mt][e] = sc[mt][e] * SC + bc; mx = fmaxf(mx, sc[mt][e]); } }
;     else { const int relb = tq + 64 * (8 - j) - 4 * g;
; #pragma unroll
;         for (int mt = 0; mt < 4; ++mt)
; #pragma unroll
;             for (int e = 0; e < 4; ++e) { int rel = relb - 16 * mt - e; rel = rel > 128 ? 128 : rel; sc[mt][e] = sc[mt][e] * SC + tb[rel + 128]; mx = fmaxf(mx, sc[mt][e]); } }
.Latt_t1_b_bc_b_done:
	v_mfma_f32_16x16x32_bf16 v[160:163], v[234:237], v[8:11], 0
	v_mfma_f32_16x16x32_bf16 v[160:163], v[238:241], v[16:19], v[160:163]
	v_mfma_f32_16x16x32_bf16 v[160:163], v[242:245], v[24:27], v[160:163]
	v_mfma_f32_16x16x32_bf16 v[160:163], v[246:249], v[32:35], v[160:163]
	s_waitcnt lgkmcnt(0)
	s_nop 7
	s_cmp_gt_i32 s37, 5
	s_cbranch_scc0 .Latt_t1_b_sm_b_cfma
	v_pk_fma_f32 v[148:149], v[148:149], s[44:45], v[218:219] op_sel_hi:[1,0,1]
	v_pk_fma_f32 v[150:151], v[150:151], s[44:45], v[220:221] op_sel_hi:[1,0,1]
	v_pk_fma_f32 v[152:153], v[152:153], s[44:45], v[222:223] op_sel_hi:[1,0,1]
	v_pk_fma_f32 v[154:155], v[154:155], s[44:45], v[224:225] op_sel_hi:[1,0,1]
	v_pk_fma_f32 v[156:157], v[156:157], s[44:45], v[226:227] op_sel_hi:[1,0,1]
	v_pk_fma_f32 v[158:159], v[158:159], s[44:45], v[228:229] op_sel_hi:[1,0,1]
	v_pk_fma_f32 v[160:161], v[160:161], s[44:45], v[230:231] op_sel_hi:[1,0,1]
	v_pk_fma_f32 v[162:163], v[162:163], s[44:45], v[232:233] op_sel_hi:[1,0,1]
	s_branch .Latt_t1_b_sm_b_fdone
.Latt_t1_b_sm_b_cfma:
	v_pk_fma_f32 v[148:149], v[148:149], s[44:45], v[218:219] op_sel_hi:[1,0,0]
	v_pk_fma_f32 v[150:151], v[150:151], s[44:45], v[218:219] op_sel_hi:[1,0,0]
	v_pk_fma_f32 v[152:153], v[152:153], s[44:45], v[218:219] op_sel_hi:[1,0,0]
	v_pk_fma_f32 v[154:155], v[154:155], s[44:45], v[218:219] op_sel_hi:[1,0,0]
	v_pk_fma_f32 v[156:157], v[156:157], s[44:45], v[218:219] op_sel_hi:[1,0,0]
	v_pk_fma_f32 v[158:159], v[158:159], s[44:45], v[218:219] op_sel_hi:[1,0,0]
	v_pk_fma_f32 v[160:161], v[160:161], s[44:45], v[218:219] op_sel_hi:[1,0,0]
	v_pk_fma_f32 v[162:163], v[162:163], s[44:45], v[218:219] op_sel_hi:[1,0,0]

; __device__ __forceinline__ unsigned cvt_pk_bf16(float lo, float hi) { unsigned r; asm volatile("v_cvt_pk_bf16_f32 %0, %1, %2" : "=v"(r) : "v"(lo), "v"(hi)); return r; }
; __device__ __forceinline__ void attn_softmax(f32x4 (&sc)[4], float& m_run, float& l_run, f32x4 (&o)[8], const int j, const int tq, const int g, const LAS float* tb, bf16x8 (&pb)[2]) {
;     ...
;     const float alpha = __builtin_amdgcn_exp2f(m_run - mx); m_run = mx;
;     float ls = 0.f;
; #pragma unroll
;     for (int mt = 0; mt < 4; ++mt)
; #pragma unroll
;         for (int e = 0; e < 4; ++e) { sc[mt][e] = __builtin_amdgcn_exp2f(sc[mt][e] - mx); ls += sc[mt][e]; }
;     l_run = l_run * alpha + ls;
;     if (__builtin_amdgcn_ballot_w64(alpha != 1.0f) != 0ull) {
; #pragma unroll
;         for (int cc = 0; cc < 8; ++cc) o[cc] *= alpha;
;     }
; #pragma unroll
;     for (int s2 = 0; s2 < 2; ++s2) { u32x4 pw; pw.x = cvt_pk_bf16(sc[2 * s2][0], sc[2 * s2][1]); pw.y = cvt_pk_bf16(sc[2 * s2][2], sc[2 * s2][3]);
;         pw.z = cvt_pk_bf16(sc[2 * s2 + 1][0], sc[2 * s2 + 1][1]); pw.w = cvt_pk_bf16(sc[2 * s2 + 1][2], sc[2 * s2 + 1][3]); pb[s2] = __builtin_bit_cast(bf16x8, pw); }
.Latt_t1_b_sm_b_norescale:
	v_pk_add_f32 v[148:149], v[148:149], v[180:181] op_sel_hi:[1,0] neg_lo:[0,1] neg_hi:[0,1]
	v_pk_add_f32 v[150:151], v[150:151], v[180:181] op_sel_hi:[1,0] neg_lo:[0,1] neg_hi:[0,1]
	v_pk_add_f32 v[152:153], v[152:153], v[180:181] op_sel_hi:[1,0] neg_lo:[0,1] neg_hi:[0,1]
	v_pk_add_f32 v[154:155], v[154:155], v[180:181] op_sel_hi:[1,0] neg_lo:[0,1] neg_hi:[0,1]
	v_pk_add_f32 v[156:157], v[156:157], v[180:181] op_sel_hi:[1,0] neg_lo:[0,1] neg_hi:[0,1]
	v_pk_add_f32 v[158:159], v[158:159], v[180:181] op_sel_hi:[1,0] neg_lo:[0,1] neg_hi:[0,1]
	v_pk_add_f32 v[160:161], v[160:161], v[180:181] op_sel_hi:[1,0] neg_lo:[0,1] neg_hi:[0,1]
	v_pk_add_f32 v[162:163], v[162:163], v[180:181] op_sel_hi:[1,0] neg_lo:[0,1] neg_hi:[0,1]
	v_exp_f32_e32 v148, v148
	v_exp_f32_e32 v149, v149
	v_exp_f32_e32 v150, v150
	v_add_f32_e32 v167, v148, v149
	v_exp_f32_e32 v151, v151
	v_add_f32_e32 v167, v150, v167
	v_exp_f32_e32 v152, v152
	v_add_f32_e32 v167, v151, v167
	v_exp_f32_e32 v153, v153
	v_add_f32_e32 v167, v152, v167
	v_exp_f32_e32 v154, v154
	v_add_f32_e32 v167, v153, v167
	v_exp_f32_e32 v155, v155
	v_add_f32_e32 v167, v154, v167
	v_exp_f32_e32 v156, v156
	v_add_f32_e32 v167, v155, v167
	v_exp_f32_e32 v157, v157
	v_add_f32_e32 v167, v156, v167
	v_exp_f32_e32 v158, v158
	v_add_f32_e32 v167, v157, v167
	v_exp_f32_e32 v159, v159
	v_add_f32_e32 v167, v158, v167
	v_exp_f32_e32 v160, v160
	v_add_f32_e32 v167, v159, v167
	v_exp_f32_e32 v161, v161
	v_add_f32_e32 v167, v160, v167
	v_exp_f32_e32 v162, v162
	v_add_f32_e32 v167, v161, v167
	v_exp_f32_e32 v163, v163
	v_add_f32_e32 v167, v162, v167
	s_nop 0
	v_add_f32_e32 v167, v163, v167
	v_fma_f32 v212, v212, v2, v167
	v_cvt_pk_bf16_f32 v148, v148, v149
	v_cvt_pk_bf16_f32 v149, v150, v151
	v_cvt_pk_bf16_f32 v150, v152, v153
	v_cvt_pk_bf16_f32 v151, v154, v155
	v_cvt_pk_bf16_f32 v152, v156, v157
	v_cvt_pk_bf16_f32 v153, v158, v159
	v_cvt_pk_bf16_f32 v154, v160, v161
	v_cvt_pk_bf16_f32 v155, v162, v163
	s_waitcnt lgkmcnt(12)
	v_mfma_f32_16x16x32_bf16 v[108:111], v[218:221], v[148:151], v[108:111]
	ds_read_b64_tr_b16 v[218:219], v179 offset:16384
	ds_read_b64_tr_b16 v[220:221], v179 offset:20480
	s_waitcnt lgkmcnt(12)
	v_mfma_f32_16x16x32_bf16 v[100:103], v[222:225], v[148:151], v[100:103]
	ds_read_b64_tr_b16 v[222:223], v172 offset:24576
	ds_read_b64_tr_b16 v[224:225], v172 offset:28672
	s_waitcnt lgkmcnt(12)
	v_mfma_f32_16x16x32_bf16 v[92:95], v[226:229], v[148:151], v[92:95]
	ds_read_b64_tr_b16 v[226:227], v173 offset:24576
	ds_read_b64_tr_b16 v[228:229], v173 offset:28672
	s_waitcnt lgkmcnt(12)
	v_mfma_f32_16x16x32_bf16 v[84:87], v[230:233], v[148:151], v[84:87]
	ds_read_b64_tr_b16 v[230:231], v174 offset:24576
	ds_read_b64_tr_b16 v[232:233], v174 offset:28672
	s_waitcnt lgkmcnt(12)
	v_mfma_f32_16x16x32_bf16 v[76:79], v[234:237], v[148:151], v[76:79]
	ds_read_b64_tr_b16 v[234:235], v175 offset:24576
	ds_read_b64_tr_b16 v[236:237], v175 offset:28672
	s_waitcnt lgkmcnt(12)
	v_mfma_f32_16x16x32_bf16 v[60:63], v[238:241], v[148:151], v[60:63]
	ds_read_b64_tr_b16 v[238:239], v176 offset:24576
	ds_read_b64_tr_b16 v[240:241], v176 offset:28672
	s_waitcnt lgkmcnt(12)
	v_mfma_f32_16x16x32_bf16 v[48:51], v[242:245], v[148:151], v[48:51]
	ds_read_b64_tr_b16 v[242:243], v177 offset:24576
	ds_read_b64_tr_b16 v[244:245], v177 offset:28672
	s_waitcnt lgkmcnt(12)
	v_mfma_f32_16x16x32_bf16 v[36:39], v[218:221], v[148:151], v[36:39]
	ds_read_b64_tr_b16 v[218:219], v178 offset:24576
	ds_read_b64_tr_b16 v[220:221], v178 offset:28672
	s_waitcnt lgkmcnt(12)
	v_mfma_f32_16x16x32_bf16 v[108:111], v[222:225], v[152:155], v[108:111]
	ds_read_b64_tr_b16 v[222:223], v179 offset:24576
	ds_read_b64_tr_b16 v[224:225], v179 offset:28672
	s_waitcnt lgkmcnt(12)
	v_mfma_f32_16x16x32_bf16 v[100:103], v[226:229], v[152:155], v[100:103]
	s_waitcnt lgkmcnt(10)
	v_mfma_f32_16x16x32_bf16 v[92:95], v[230:233], v[152:155], v[92:95]
	s_waitcnt lgkmcnt(8)
	v_mfma_f32_16x16x32_bf16 v[84:87], v[234:237], v[152:155], v[84:87]
	s_waitcnt lgkmcnt(6)
	v_mfma_f32_16x16x32_bf16 v[76:79], v[238:241], v[152:155], v[76:79]
	s_waitcnt lgkmcnt(4)
	v_mfma_f32_16x16x32_bf16 v[60:63], v[242:245], v[152:155], v[60:63]
	s_waitcnt lgkmcnt(2)
	v_mfma_f32_16x16x32_bf16 v[48:51], v[218:221], v[152:155], v[48:51]
	s_waitcnt lgkmcnt(0)
	v_mfma_f32_16x16x32_bf16 v[36:39], v[222:225], v[152:155], v[36:39]
	v_mov_b32_e32 v217, v215
	s_branch .LBB0_365

; __device__ void attn_quad(const bf16_t* proj, const float* rel_bias, bf16_t* ycat, int quad, LAS unsigned char* lds, const int WID) {
;     ...
;         ATT_COMPUTE(u + 1);
.LBB0_367:
	s_add_i32 s10, s63, -2
	s_cmp_ge_u32 s10, s93
	s_cselect_b64 s[10:11], -1, 0
	s_cmp_lt_u32 s74, s20
	s_cselect_b64 s[12:13], -1, 0
	s_and_b64 s[10:11], s[10:11], s[12:13]
	s_cmp_lt_u32 s74, s21
	s_cselect_b64 s[12:13], -1, 0
	s_and_b64 s[8:9], s[8:9], s[12:13]
	s_or_b64 s[12:13], s[10:11], s[8:9]
	s_andn2_b64 vcc, exec, s[12:13]
	s_cbranch_vccnz .LBB0_371
	s_and_b64 s[28:29], s[10:11], s[8:9]
	s_cbranch_scc1 .Latt_t2_ab
	s_and_b64 vcc, exec, s[10:11]
	s_cbranch_vccnz .Latt_t2_a
	s_branch .Latt_t2_b

; __device__ __forceinline__ void attn_softmax(f32x4 (&sc)[4], float& m_run, float& l_run, f32x4 (&o)[8], const int j, const int tq, const int g, const LAS float* tb, bf16x8 (&pb)[2]) {
;     ...
;     else { const int relb = tq + 64 * (8 - j) - 4 * g;
; #pragma unroll
;         for (int mt = 0; mt < 4; ++mt)
; #pragma unroll
;             for (int e = 0; e < 4; ++e) { int rel = relb - 16 * mt - e; rel = rel > 128 ? 128 : rel; sc[mt][e] = sc[mt][e] * SC + tb[rel + 128]; mx = fmaxf(mx, sc[mt][e]); } }
.Latt_t2_ab:
	s_sub_i32 s36, s74, s93
	s_add_i32 s36, s36, 1
	s_add_i32 s37, s36, -1
	v_add_u32_e32 v164, v187, v189
	v_add_u32_e32 v165, v187, v190
	v_add_u32_e32 v166, v187, v191
	ds_read_b128 v[218:221], v211 offset:32768
	ds_read_b128 v[222:225], v164 offset:32768
	ds_read_b128 v[226:229], v165 offset:32768
	ds_read_b128 v[230:233], v166 offset:32768
	ds_read_b128 v[234:237], v211 offset:36864
	ds_read_b128 v[238:241], v164 offset:36864
	ds_read_b128 v[242:245], v165 offset:36864
	ds_read_b128 v[246:249], v166 offset:36864
	s_waitcnt lgkmcnt(7)
	v_mfma_f32_16x16x32_bf16 v[132:135], v[218:221], v[4:7], 0
	v_mfma_f32_16x16x32_bf16 v[148:151], v[218:221], v[8:11], 0
	ds_read_b128 v[218:221], v211 offset:40960
	s_waitcnt lgkmcnt(7)
	v_mfma_f32_16x16x32_bf16 v[132:135], v[222:225], v[12:15], v[132:135]
	v_mfma_f32_16x16x32_bf16 v[148:151], v[222:225], v[16:19], v[148:151]
	ds_read_b128 v[222:225], v164 offset:40960
	s_waitcnt lgkmcnt(7)
	v_mfma_f32_16x16x32_bf16 v[132:135], v[226:229], v[20:23], v[132:135]
	v_mfma_f32_16x16x32_bf16 v[148:151], v[226:229], v[24:27], v[148:151]
	ds_read_b128 v[226:229], v165 offset:40960
	s_waitcnt lgkmcnt(7)
	v_mfma_f32_16x16x32_bf16 v[132:135], v[230:233], v[28:31], v[132:135]
	v_mfma_f32_16x16x32_bf16 v[148:151], v[230:233], v[32:35], v[148:151]
	ds_read_b128 v[230:233], v166 offset:40960
	s_waitcnt lgkmcnt(7)
	v_mfma_f32_16x16x32_bf16 v[136:139], v[234:237], v[4:7], 0
	v_mfma_f32_16x16x32_bf16 v[152:155], v[234:237], v[8:11], 0
	ds_read_b128 v[234:237], v211 offset:45056
	s_waitcnt lgkmcnt(7)
	v_mfma_f32_16x16x32_bf16 v[136:139], v[238:241], v[12:15], v[136:139]
	v_mfma_f32_16x16x32_bf16 v[152:155], v[238:241], v[16:19], v[152:155]
	ds_read_b128 v[238:241], v164 offset:45056
	s_waitcnt lgkmcnt(7)
	v_mfma_f32_16x16x32_bf16 v[136:139], v[242:245], v[20:23], v[136:139]
	v_mfma_f32_16x16x32_bf16 v[152:155], v[242:245], v[24:27], v[152:155]
	ds_read_b128 v[242:245], v165 offset:45056
	s_waitcnt lgkmcnt(7)
	v_mfma_f32_16x16x32_bf16 v[136:139], v[246:249], v[28:31], v[136:139]
	v_mfma_f32_16x16x32_bf16 v[152:155], v[246:249], v[32:35], v[152:155]
	ds_read_b128 v[246:249], v166 offset:45056
	s_waitcnt lgkmcnt(7)
	v_mfma_f32_16x16x32_bf16 v[140:143], v[218:221], v[4:7], 0
	v_mfma_f32_16x16x32_bf16 v[156:159], v[218:221], v[8:11], 0
	s_waitcnt lgkmcnt(6)
	v_mfma_f32_16x16x32_bf16 v[140:143], v[222:225], v[12:15], v[140:143]
	v_mfma_f32_16x16x32_bf16 v[156:159], v[222:225], v[16:19], v[156:159]
	s_waitcnt lgkmcnt(5)
	v_mfma_f32_16x16x32_bf16 v[140:143], v[226:229], v[20:23], v[140:143]
	v_mfma_f32_16x16x32_bf16 v[156:159], v[226:229], v[24:27], v[156:159]
	s_waitcnt lgkmcnt(4)
	v_mfma_f32_16x16x32_bf16 v[140:143], v[230:233], v[28:31], v[140:143]
	v_mfma_f32_16x16x32_bf16 v[156:159], v[230:233], v[32:35], v[156:159]
	s_waitcnt lgkmcnt(0)
	s_cmp_gt_i32 s36, 5
	s_cbranch_scc0 .Latt_t2_ab_bc_a_const
	s_mov_b32 s38, 0x10000
	v_lshl_add_u32 v1, v210, 2, s38
	v_min_i32_e32 v218, 0x10400, v1
	v_add_u32_e32 v219, 0xfffffffc, v1
	v_min_i32_e32 v219, 0x10400, v219
	v_add_u32_e32 v220, 0xfffffff8, v1
	v_min_i32_e32 v220, 0x10400, v220
	v_add_u32_e32 v221, 0xfffffff4, v1
	v_min_i32_e32 v221, 0x10400, v221
	v_add_u32_e32 v222, 0xffffffc0, v1
	v_min_i32_e32 v222, 0x10400, v222
	v_add_u32_e32 v223, 0xffffffbc, v1
	v_min_i32_e32 v223, 0x10400, v223
	v_add_u32_e32 v224, 0xffffffb8, v1
	v_min_i32_e32 v224, 0x10400, v224
	v_add_u32_e32 v225, 0xffffffb4, v1
	v_min_i32_e32 v225, 0x10400, v225
	v_add_u32_e32 v226, 0xffffff80, v1
	v_min_i32_e32 v226, 0x10400, v226
	v_add_u32_e32 v227, 0xffffff7c, v1
	v_min_i32_e32 v227, 0x10400, v227
	v_add_u32_e32 v228, 0xffffff78, v1
	v_min_i32_e32 v228, 0x10400, v228
	v_add_u32_e32 v229, 0xffffff74, v1
	v_min_i32_e32 v229, 0x10400, v229
	v_add_u32_e32 v230, 0xffffff40, v1
	v_min_i32_e32 v230, 0x10400, v230
	v_add_u32_e32 v231, 0xffffff3c, v1
	v_min_i32_e32 v231, 0x10400, v231
	v_add_u32_e32 v232, 0xffffff38, v1
	v_min_i32_e32 v232, 0x10400, v232
	v_add_u32_e32 v233, 0xffffff34, v1
	v_min_i32_e32 v233, 0x10400, v233
	ds_read_b32 v218, v218
	ds_read_b32 v219, v219
	ds_read_b32 v220, v220
	ds_read_b32 v221, v221
	ds_read_b32 v222, v222
	ds_read_b32 v223, v223
	ds_read_b32 v224, v224
	ds_read_b32 v225, v225
	ds_read_b32 v226, v226
	ds_read_b32 v227, v227
	ds_read_b32 v228, v228
	ds_read_b32 v229, v229
	ds_read_b32 v230, v230
	ds_read_b32 v231, v231
	ds_read_b32 v232, v232
	ds_read_b32 v233, v233
	s_branch .Latt_t2_ab_bc_a_done

; __device__ __forceinline__ void attn_softmax(f32x4 (&sc)[4], float& m_run, float& l_run, f32x4 (&o)[8], const int j, const int tq, const int g, const LAS float* tb, bf16x8 (&pb)[2]) {
;     ...
;     else { const int relb = tq + 64 * (8 - j) - 4 * g;
; #pragma unroll
;         for (int mt = 0; mt < 4; ++mt)
; #pragma unroll
;             for (int e = 0; e < 4; ++e) { int rel = relb - 16 * mt - e; rel = rel > 128 ? 128 : rel; sc[mt][e] = sc[mt][e] * SC + tb[rel + 128]; mx = fmaxf(mx, sc[mt][e]); } }
.Latt_t2_ab_bc_a_done:
	v_mfma_f32_16x16x32_bf16 v[144:147], v[234:237], v[4:7], 0
	v_mfma_f32_16x16x32_bf16 v[160:163], v[234:237], v[8:11], 0
	v_mfma_f32_16x16x32_bf16 v[144:147], v[238:241], v[12:15], v[144:147]
	v_mfma_f32_16x16x32_bf16 v[160:163], v[238:241], v[16:19], v[160:163]
	v_mfma_f32_16x16x32_bf16 v[144:147], v[242:245], v[20:23], v[144:147]
	v_mfma_f32_16x16x32_bf16 v[160:163], v[242:245], v[24:27], v[160:163]
	v_mfma_f32_16x16x32_bf16 v[144:147], v[246:249], v[28:31], v[144:147]
	v_mfma_f32_16x16x32_bf16 v[160:163], v[246:249], v[32:35], v[160:163]
	s_waitcnt lgkmcnt(0)
	s_cmp_gt_i32 s37, 5
	s_cbranch_scc0 .Latt_t2_ab_bc_b_const
	s_mov_b32 s38, 0x10100
	v_lshl_add_u32 v1, v210, 2, s38
	v_min_i32_e32 v234, 0x10400, v1
	v_add_u32_e32 v235, 0xfffffffc, v1
	v_min_i32_e32 v235, 0x10400, v235
	v_add_u32_e32 v236, 0xfffffff8, v1
	v_min_i32_e32 v236, 0x10400, v236
	v_add_u32_e32 v237, 0xfffffff4, v1
	v_min_i32_e32 v237, 0x10400, v237
	v_add_u32_e32 v238, 0xffffffc0, v1
	v_min_i32_e32 v238, 0x10400, v238
	v_add_u32_e32 v239, 0xffffffbc, v1
	v_min_i32_e32 v239, 0x10400, v239
	v_add_u32_e32 v240, 0xffffffb8, v1
	v_min_i32_e32 v240, 0x10400, v240
	v_add_u32_e32 v241, 0xffffffb4, v1
	v_min_i32_e32 v241, 0x10400, v241
	v_add_u32_e32 v242, 0xffffff80, v1
	v_min_i32_e32 v242, 0x10400, v242
	v_add_u32_e32 v243, 0xffffff7c, v1
	v_min_i32_e32 v243, 0x10400, v243
	v_add_u32_e32 v244, 0xffffff78, v1
	v_min_i32_e32 v244, 0x10400, v244
	v_add_u32_e32 v245, 0xffffff74, v1
	v_min_i32_e32 v245, 0x10400, v245
	v_add_u32_e32 v246, 0xffffff40, v1
	v_min_i32_e32 v246, 0x10400, v246
	v_add_u32_e32 v247, 0xffffff3c, v1
	v_min_i32_e32 v247, 0x10400, v247
	v_add_u32_e32 v248, 0xffffff38, v1
	v_min_i32_e32 v248, 0x10400, v248
	v_add_u32_e32 v249, 0xffffff34, v1
	v_min_i32_e32 v249, 0x10400, v249
	ds_read_b32 v234, v234
	ds_read_b32 v235, v235
	ds_read_b32 v236, v236
	ds_read_b32 v237, v237
	ds_read_b32 v238, v238
	ds_read_b32 v239, v239
	ds_read_b32 v240, v240
	ds_read_b32 v241, v241
	ds_read_b32 v242, v242
	ds_read_b32 v243, v243
	ds_read_b32 v244, v244
	ds_read_b32 v245, v245
	ds_read_b32 v246, v246
	ds_read_b32 v247, v247
	ds_read_b32 v248, v248
	ds_read_b32 v249, v249
	s_branch .Latt_t2_ab_bc_b_done

; __device__ __forceinline__ void attn_softmax(f32x4 (&sc)[4], float& m_run, float& l_run, f32x4 (&o)[8], const int j, const int tq, const int g, const LAS float* tb, bf16x8 (&pb)[2]) {
;     ...
;     mx = fmaxf(mx, __shfl_xor(mx, 16)); mx = fmaxf(mx, __shfl_xor(mx, 32));
;     const float alpha = __builtin_amdgcn_exp2f(m_run - mx); m_run = mx;
;     float ls = 0.f;
; #pragma unroll
;     for (int mt = 0; mt < 4; ++mt)
; #pragma unroll
;         for (int e = 0; e < 4; ++e) { sc[mt][e] = __builtin_amdgcn_exp2f(sc[mt][e] - mx); ls += sc[mt][e]; }
;     l_run = l_run * alpha + ls;
;     if (__builtin_amdgcn_ballot_w64(alpha != 1.0f) != 0ull) {
; #pragma unroll
;         for (int cc = 0; cc < 8; ++cc) o[cc] *= alpha;
;     }
.Latt_t2_ab_sm_a_fdone:
	v_max3_f32 v1, v217, v132, v133
	v_max3_f32 v1, v1, v134, v135
	v_max3_f32 v1, v1, v136, v137
	v_max3_f32 v1, v1, v138, v139
	v_max3_f32 v1, v1, v140, v141
	v_max3_f32 v1, v1, v142, v143
	v_max3_f32 v1, v1, v144, v145
	v_max3_f32 v1, v1, v146, v147
	v_mov_b32_e32 v3, v1
	s_nop 1
	v_permlane16_swap_b32_e32 v3, v1
	v_max_f32_e32 v1, v1, v3
	v_mov_b32_e32 v3, v1
	s_nop 1
	v_permlane32_swap_b32_e32 v3, v1
	v_max_f32_e32 v215, v1, v3
	v_sub_f32_e32 v1, v217, v215
	v_exp_f32_e32 v2, v1
	v_mov_b32_e32 v180, v215
	v_cmp_neq_f32_e32 vcc, 1.0, v2
	s_cbranch_vccz .Latt_t2_ab_sm_a_norescale
	v_pk_mul_f32 v[112:113], v[112:113], v[2:3] op_sel_hi:[1,0]
	v_pk_mul_f32 v[114:115], v[114:115], v[2:3] op_sel_hi:[1,0]
	v_pk_mul_f32 v[104:105], v[104:105], v[2:3] op_sel_hi:[1,0]
	v_pk_mul_f32 v[106:107], v[106:107], v[2:3] op_sel_hi:[1,0]
	v_pk_mul_f32 v[96:97], v[96:97], v[2:3] op_sel_hi:[1,0]
	v_pk_mul_f32 v[98:99], v[98:99], v[2:3] op_sel_hi:[1,0]
	v_pk_mul_f32 v[88:89], v[88:89], v[2:3] op_sel_hi:[1,0]
	v_pk_mul_f32 v[90:91], v[90:91], v[2:3] op_sel_hi:[1,0]
	v_pk_mul_f32 v[80:81], v[80:81], v[2:3] op_sel_hi:[1,0]
	v_pk_mul_f32 v[82:83], v[82:83], v[2:3] op_sel_hi:[1,0]
	v_pk_mul_f32 v[64:65], v[64:65], v[2:3] op_sel_hi:[1,0]
	v_pk_mul_f32 v[66:67], v[66:67], v[2:3] op_sel_hi:[1,0]
	v_pk_mul_f32 v[52:53], v[52:53], v[2:3] op_sel_hi:[1,0]
	v_pk_mul_f32 v[54:55], v[54:55], v[2:3] op_sel_hi:[1,0]
	v_pk_mul_f32 v[40:41], v[40:41], v[2:3] op_sel_hi:[1,0]
	v_pk_mul_f32 v[42:43], v[42:43], v[2:3] op_sel_hi:[1,0]

; __device__ __forceinline__ unsigned cvt_pk_bf16(float lo, float hi) { unsigned r; asm volatile("v_cvt_pk_bf16_f32 %0, %1, %2" : "=v"(r) : "v"(lo), "v"(hi)); return r; }
; __device__ __forceinline__ void attn_softmax(f32x4 (&sc)[4], float& m_run, float& l_run, f32x4 (&o)[8], const int j, const int tq, const int g, const LAS float* tb, bf16x8 (&pb)[2]) {
;     ...
;     mx = fmaxf(mx, __shfl_xor(mx, 16)); mx = fmaxf(mx, __shfl_xor(mx, 32));
;     const float alpha = __builtin_amdgcn_exp2f(m_run - mx); m_run = mx;
;     float ls = 0.f;
; #pragma unroll
;     for (int mt = 0; mt < 4; ++mt)
; #pragma unroll
;         for (int e = 0; e < 4; ++e) { sc[mt][e] = __builtin_amdgcn_exp2f(sc[mt][e] - mx); ls += sc[mt][e]; }
;     l_run = l_run * alpha + ls;
;     if (__builtin_amdgcn_ballot_w64(alpha != 1.0f) != 0ull) {
; #pragma unroll
;         for (int cc = 0; cc < 8; ++cc) o[cc] *= alpha;
;     }
; #pragma unroll
;     for (int s2 = 0; s2 < 2; ++s2) { u32x4 pw; pw.x = cvt_pk_bf16(sc[2 * s2][0], sc[2 * s2][1]); pw.y = cvt_pk_bf16(sc[2 * s2][2], sc[2 * s2][3]);
;         pw.z = cvt_pk_bf16(sc[2 * s2 + 1][0], sc[2 * s2 + 1][1]); pw.w = cvt_pk_bf16(sc[2 * s2 + 1][2], sc[2 * s2 + 1][3]); pb[s2] = __builtin_bit_cast(bf16x8, pw); }
.Latt_t2_ab_sm_b_fdone:
	v_add_u32_e32 v172, v192, v193
	v_add_u32_e32 v173, v192, v195
	v_add_u32_e32 v174, v192, v197
	v_add_u32_e32 v175, v192, v199
	v_add_u32_e32 v176, v192, v201
	v_add_u32_e32 v177, v192, v203
	v_add_u32_e32 v178, v192, v205
	v_add_u32_e32 v179, v192, v207
	ds_read_b64_tr_b16 v[218:219], v172 offset:49152
	ds_read_b64_tr_b16 v[220:221], v172 offset:53248
	ds_read_b64_tr_b16 v[222:223], v173 offset:49152
	ds_read_b64_tr_b16 v[224:225], v173 offset:53248
	ds_read_b64_tr_b16 v[226:227], v174 offset:49152
	ds_read_b64_tr_b16 v[228:229], v174 offset:53248
	ds_read_b64_tr_b16 v[230:231], v175 offset:49152
	ds_read_b64_tr_b16 v[232:233], v175 offset:53248
	ds_read_b64_tr_b16 v[234:235], v176 offset:49152
	ds_read_b64_tr_b16 v[236:237], v176 offset:53248
	ds_read_b64_tr_b16 v[238:239], v177 offset:49152
	ds_read_b64_tr_b16 v[240:241], v177 offset:53248
	ds_read_b64_tr_b16 v[242:243], v178 offset:49152
	ds_read_b64_tr_b16 v[244:245], v178 offset:53248
	v_max3_f32 v1, v216, v148, v149
	v_max3_f32 v1, v1, v150, v151
	v_max3_f32 v1, v1, v152, v153
	v_max3_f32 v1, v1, v154, v155
	v_max3_f32 v1, v1, v156, v157
	v_max3_f32 v1, v1, v158, v159
	v_max3_f32 v1, v1, v160, v161
	v_max3_f32 v1, v1, v162, v163
	v_mov_b32_e32 v3, v1
	s_nop 1
	v_permlane16_swap_b32_e32 v3, v1
	v_max_f32_e32 v1, v1, v3
	v_mov_b32_e32 v3, v1
	s_nop 1
	v_permlane32_swap_b32_e32 v3, v1
	v_max_f32_e32 v214, v1, v3
	v_sub_f32_e32 v1, v216, v214
	v_exp_f32_e32 v2, v1
	v_mov_b32_e32 v180, v214
	v_cmp_neq_f32_e32 vcc, 1.0, v2
	s_cbranch_vccz .Latt_t2_ab_sm_b_norescale
	v_pk_mul_f32 v[108:109], v[108:109], v[2:3] op_sel_hi:[1,0]
	v_pk_mul_f32 v[110:111], v[110:111], v[2:3] op_sel_hi:[1,0]
	v_pk_mul_f32 v[100:101], v[100:101], v[2:3] op_sel_hi:[1,0]
	v_pk_mul_f32 v[102:103], v[102:103], v[2:3] op_sel_hi:[1,0]
	v_pk_mul_f32 v[92:93], v[92:93], v[2:3] op_sel_hi:[1,0]
	v_pk_mul_f32 v[94:95], v[94:95], v[2:3] op_sel_hi:[1,0]
	v_pk_mul_f32 v[84:85], v[84:85], v[2:3] op_sel_hi:[1,0]
	v_pk_mul_f32 v[86:87], v[86:87], v[2:3] op_sel_hi:[1,0]
	v_pk_mul_f32 v[76:77], v[76:77], v[2:3] op_sel_hi:[1,0]
	v_pk_mul_f32 v[78:79], v[78:79], v[2:3] op_sel_hi:[1,0]
	v_pk_mul_f32 v[60:61], v[60:61], v[2:3] op_sel_hi:[1,0]
	v_pk_mul_f32 v[62:63], v[62:63], v[2:3] op_sel_hi:[1,0]
	v_pk_mul_f32 v[48:49], v[48:49], v[2:3] op_sel_hi:[1,0]
	v_pk_mul_f32 v[50:51], v[50:51], v[2:3] op_sel_hi:[1,0]
	v_pk_mul_f32 v[36:37], v[36:37], v[2:3] op_sel_hi:[1,0]
	v_pk_mul_f32 v[38:39], v[38:39], v[2:3] op_sel_hi:[1,0]
.Latt_t2_ab_sm_b_norescale:
	v_pk_add_f32 v[148:149], v[148:149], v[180:181] op_sel_hi:[1,0] neg_lo:[0,1] neg_hi:[0,1]
	v_pk_add_f32 v[150:151], v[150:151], v[180:181] op_sel_hi:[1,0] neg_lo:[0,1] neg_hi:[0,1]
	v_pk_add_f32 v[152:153], v[152:153], v[180:181] op_sel_hi:[1,0] neg_lo:[0,1] neg_hi:[0,1]
	v_pk_add_f32 v[154:155], v[154:155], v[180:181] op_sel_hi:[1,0] neg_lo:[0,1] neg_hi:[0,1]
	v_pk_add_f32 v[156:157], v[156:157], v[180:181] op_sel_hi:[1,0] neg_lo:[0,1] neg_hi:[0,1]
	v_pk_add_f32 v[158:159], v[158:159], v[180:181] op_sel_hi:[1,0] neg_lo:[0,1] neg_hi:[0,1]
	v_pk_add_f32 v[160:161], v[160:161], v[180:181] op_sel_hi:[1,0] neg_lo:[0,1] neg_hi:[0,1]
	v_pk_add_f32 v[162:163], v[162:163], v[180:181] op_sel_hi:[1,0] neg_lo:[0,1] neg_hi:[0,1]
	v_exp_f32_e32 v148, v148
	v_exp_f32_e32 v149, v149
	v_exp_f32_e32 v150, v150
	v_add_f32_e32 v167, v148, v149
	v_exp_f32_e32 v151, v151
	v_add_f32_e32 v167, v150, v167
	v_exp_f32_e32 v152, v152
	v_add_f32_e32 v167, v151, v167
	v_exp_f32_e32 v153, v153
	v_add_f32_e32 v167, v152, v167
	v_exp_f32_e32 v154, v154
	v_add_f32_e32 v167, v153, v167
	v_exp_f32_e32 v155, v155
	v_add_f32_e32 v167, v154, v167
	v_exp_f32_e32 v156, v156
	v_add_f32_e32 v167, v155, v167
	v_exp_f32_e32 v157, v157
	v_add_f32_e32 v167, v156, v167
	v_exp_f32_e32 v158, v158
	v_add_f32_e32 v167, v157, v167
	v_exp_f32_e32 v159, v159
	v_add_f32_e32 v167, v158, v167
	v_exp_f32_e32 v160, v160
	v_add_f32_e32 v167, v159, v167
	v_exp_f32_e32 v161, v161
	v_add_f32_e32 v167, v160, v167
	v_exp_f32_e32 v162, v162
	v_add_f32_e32 v167, v161, v167
	v_exp_f32_e32 v163, v163
	v_add_f32_e32 v167, v162, v167
	s_nop 0
	v_add_f32_e32 v167, v163, v167
	v_fma_f32 v212, v212, v2, v167
	v_cvt_pk_bf16_f32 v148, v148, v149
	v_cvt_pk_bf16_f32 v149, v150, v151
	v_cvt_pk_bf16_f32 v150, v152, v153
	v_cvt_pk_bf16_f32 v151, v154, v155
	v_cvt_pk_bf16_f32 v152, v156, v157
	v_cvt_pk_bf16_f32 v153, v158, v159
	v_cvt_pk_bf16_f32 v154, v160, v161
	v_cvt_pk_bf16_f32 v155, v162, v163
	s_waitcnt lgkmcnt(12)
	v_mfma_f32_16x16x32_bf16 v[112:115], v[218:221], v[132:135], v[112:115]
	v_mfma_f32_16x16x32_bf16 v[108:111], v[218:221], v[148:151], v[108:111]
	ds_read_b64_tr_b16 v[218:219], v179 offset:49152
	ds_read_b64_tr_b16 v[220:221], v179 offset:53248
	s_waitcnt lgkmcnt(12)
	v_mfma_f32_16x16x32_bf16 v[104:107], v[222:225], v[132:135], v[104:107]
	v_mfma_f32_16x16x32_bf16 v[100:103], v[222:225], v[148:151], v[100:103]
	ds_read_b64_tr_b16 v[222:223], v172 offset:57344
	ds_read_b64_tr_b16 v[224:225], v172 offset:61440
	s_waitcnt lgkmcnt(12)
	v_mfma_f32_16x16x32_bf16 v[96:99], v[226:229], v[132:135], v[96:99]
	v_mfma_f32_16x16x32_bf16 v[92:95], v[226:229], v[148:151], v[92:95]
	ds_read_b64_tr_b16 v[226:227], v173 offset:57344
	ds_read_b64_tr_b16 v[228:229], v173 offset:61440
	s_waitcnt lgkmcnt(12)
	v_mfma_f32_16x16x32_bf16 v[88:91], v[230:233], v[132:135], v[88:91]
	v_mfma_f32_16x16x32_bf16 v[84:87], v[230:233], v[148:151], v[84:87]
	ds_read_b64_tr_b16 v[230:231], v174 offset:57344
	ds_read_b64_tr_b16 v[232:233], v174 offset:61440
	s_waitcnt lgkmcnt(12)
; #define ATT_STORE(buf_, KR, VR) do { _Pragma("unroll") for (int _i = 0; _i < 2; ++_i) { const unsigned ob_ = off_b(srow, sch + 8 * _i); \
;         *(LAS u32x4*)(lds + (buf_) * 32768 + ob_) = KR[_i]; *(LAS u32x4*)(lds + (buf_) * 32768 + 16384 + ob_) = VR[_i]; } } while (0)
; __device__ void attn_quad(const bf16_t* proj, const float* rel_bias, bf16_t* ycat, int quad, LAS unsigned char* lds, const int WID) {
;     ...
;         ATT_COMPUTE(u + 1);
;         if (u + 2 < 12) ATT_STORE(buf ^ 1, kr0, vr0);
;         __syncthreads(); buf ^= 1;
	v_mfma_f32_16x16x32_bf16 v[80:83], v[234:237], v[132:135], v[80:83]
	v_mfma_f32_16x16x32_bf16 v[76:79], v[234:237], v[148:151], v[76:79]
	ds_read_b64_tr_b16 v[234:235], v175 offset:57344
	ds_read_b64_tr_b16 v[236:237], v175 offset:61440
	s_waitcnt lgkmcnt(12)
	v_mfma_f32_16x16x32_bf16 v[64:67], v[238:241], v[132:135], v[64:67]
	v_mfma_f32_16x16x32_bf16 v[60:63], v[238:241], v[148:151], v[60:63]
	ds_read_b64_tr_b16 v[238:239], v176 offset:57344
	ds_read_b64_tr_b16 v[240:241], v176 offset:61440
	s_waitcnt lgkmcnt(12)
	v_mfma_f32_16x16x32_bf16 v[52:55], v[242:245], v[132:135], v[52:55]
	v_mfma_f32_16x16x32_bf16 v[48:51], v[242:245], v[148:151], v[48:51]
	ds_read_b64_tr_b16 v[242:243], v177 offset:57344
	ds_read_b64_tr_b16 v[244:245], v177 offset:61440
	s_waitcnt lgkmcnt(12)
	v_mfma_f32_16x16x32_bf16 v[40:43], v[218:221], v[132:135], v[40:43]
	v_mfma_f32_16x16x32_bf16 v[36:39], v[218:221], v[148:151], v[36:39]
	ds_read_b64_tr_b16 v[218:219], v178 offset:57344
	ds_read_b64_tr_b16 v[220:221], v178 offset:61440
	s_waitcnt lgkmcnt(12)
	v_mfma_f32_16x16x32_bf16 v[112:115], v[222:225], v[136:139], v[112:115]
	v_mfma_f32_16x16x32_bf16 v[108:111], v[222:225], v[152:155], v[108:111]
	ds_read_b64_tr_b16 v[222:223], v179 offset:57344
	ds_read_b64_tr_b16 v[224:225], v179 offset:61440
	s_waitcnt lgkmcnt(12)
	v_mfma_f32_16x16x32_bf16 v[104:107], v[226:229], v[136:139], v[104:107]
	v_mfma_f32_16x16x32_bf16 v[100:103], v[226:229], v[152:155], v[100:103]
	s_waitcnt lgkmcnt(10)
	v_mfma_f32_16x16x32_bf16 v[96:99], v[230:233], v[136:139], v[96:99]
	v_mfma_f32_16x16x32_bf16 v[92:95], v[230:233], v[152:155], v[92:95]
	s_waitcnt lgkmcnt(8)
	v_mfma_f32_16x16x32_bf16 v[88:91], v[234:237], v[136:139], v[88:91]
	v_mfma_f32_16x16x32_bf16 v[84:87], v[234:237], v[152:155], v[84:87]
	s_waitcnt lgkmcnt(6)
	v_mfma_f32_16x16x32_bf16 v[80:83], v[238:241], v[136:139], v[80:83]
	v_mfma_f32_16x16x32_bf16 v[76:79], v[238:241], v[152:155], v[76:79]
	s_waitcnt lgkmcnt(4)
	v_mfma_f32_16x16x32_bf16 v[64:67], v[242:245], v[136:139], v[64:67]
	v_mfma_f32_16x16x32_bf16 v[60:63], v[242:245], v[152:155], v[60:63]
	s_waitcnt lgkmcnt(2)
	v_mfma_f32_16x16x32_bf16 v[52:55], v[218:221], v[136:139], v[52:55]
	v_mfma_f32_16x16x32_bf16 v[48:51], v[218:221], v[152:155], v[48:51]
	s_waitcnt lgkmcnt(0)
	v_mfma_f32_16x16x32_bf16 v[40:43], v[222:225], v[136:139], v[40:43]
	v_mfma_f32_16x16x32_bf16 v[36:39], v[222:225], v[152:155], v[36:39]
	s_andn2_b64 vcc, exec, s[46:47]
	s_cbranch_vccnz .LBB0_232
	s_branch .LBB0_514
.Latt_t2_a:
	s_sub_i32 s36, s74, s93
	s_add_i32 s36, s36, 1
	s_add_i32 s37, s36, -1
	v_add_u32_e32 v164, v187, v189
	v_add_u32_e32 v165, v187, v190
	v_add_u32_e32 v166, v187, v191
	ds_read_b128 v[218:221], v211 offset:32768
	ds_read_b128 v[222:225], v164 offset:32768
	ds_read_b128 v[226:229], v165 offset:32768
	ds_read_b128 v[230:233], v166 offset:32768
	ds_read_b128 v[234:237], v211 offset:36864
	ds_read_b128 v[238:241], v164 offset:36864
	ds_read_b128 v[242:245], v165 offset:36864
	ds_read_b128 v[246:249], v166 offset:36864
	s_waitcnt lgkmcnt(7)
	v_mfma_f32_16x16x32_bf16 v[132:135], v[218:221], v[4:7], 0
	ds_read_b128 v[218:221], v211 offset:40960
	s_waitcnt lgkmcnt(7)
	v_mfma_f32_16x16x32_bf16 v[132:135], v[222:225], v[12:15], v[132:135]
	ds_read_b128 v[222:225], v164 offset:40960
	s_waitcnt lgkmcnt(7)
	v_mfma_f32_16x16x32_bf16 v[132:135], v[226:229], v[20:23], v[132:135]
	ds_read_b128 v[226:229], v165 offset:40960
	s_waitcnt lgkmcnt(7)
	v_mfma_f32_16x16x32_bf16 v[132:135], v[230:233], v[28:31], v[132:135]
	ds_read_b128 v[230:233], v166 offset:40960
	s_waitcnt lgkmcnt(7)
	v_mfma_f32_16x16x32_bf16 v[136:139], v[234:237], v[4:7], 0
	ds_read_b128 v[234:237], v211 offset:45056
	s_waitcnt lgkmcnt(7)
	v_mfma_f32_16x16x32_bf16 v[136:139], v[238:241], v[12:15], v[136:139]
	ds_read_b128 v[238:241], v164 offset:45056
	s_waitcnt lgkmcnt(7)
	v_mfma_f32_16x16x32_bf16 v[136:139], v[242:245], v[20:23], v[136:139]
	ds_read_b128 v[242:245], v165 offset:45056
	s_waitcnt lgkmcnt(7)
	v_mfma_f32_16x16x32_bf16 v[136:139], v[246:249], v[28:31], v[136:139]
	ds_read_b128 v[246:249], v166 offset:45056
	s_waitcnt lgkmcnt(7)
	v_mfma_f32_16x16x32_bf16 v[140:143], v[218:221], v[4:7], 0
	s_waitcnt lgkmcnt(6)
	v_mfma_f32_16x16x32_bf16 v[140:143], v[222:225], v[12:15], v[140:143]
	s_waitcnt lgkmcnt(5)
	v_mfma_f32_16x16x32_bf16 v[140:143], v[226:229], v[20:23], v[140:143]
	s_waitcnt lgkmcnt(4)
	v_mfma_f32_16x16x32_bf16 v[140:143], v[230:233], v[28:31], v[140:143]
	s_waitcnt lgkmcnt(0)
	s_cmp_gt_i32 s36, 5
	s_cbranch_scc0 .Latt_t2_a_bc_a_const
	s_mov_b32 s38, 0x10000
	v_lshl_add_u32 v1, v210, 2, s38
	v_min_i32_e32 v218, 0x10400, v1
	v_add_u32_e32 v219, 0xfffffffc, v1
	v_min_i32_e32 v219, 0x10400, v219
	v_add_u32_e32 v220, 0xfffffff8, v1
	v_min_i32_e32 v220, 0x10400, v220
	v_add_u32_e32 v221, 0xfffffff4, v1
	v_min_i32_e32 v221, 0x10400, v221
	v_add_u32_e32 v222, 0xffffffc0, v1
	v_min_i32_e32 v222, 0x10400, v222
	v_add_u32_e32 v223, 0xffffffbc, v1
	v_min_i32_e32 v223, 0x10400, v223
	v_add_u32_e32 v224, 0xffffffb8, v1
	v_min_i32_e32 v224, 0x10400, v224
	v_add_u32_e32 v225, 0xffffffb4, v1
	v_min_i32_e32 v225, 0x10400, v225
	v_add_u32_e32 v226, 0xffffff80, v1
	v_min_i32_e32 v226, 0x10400, v226
	v_add_u32_e32 v227, 0xffffff7c, v1
	v_min_i32_e32 v227, 0x10400, v227
	v_add_u32_e32 v228, 0xffffff78, v1
	v_min_i32_e32 v228, 0x10400, v228
	v_add_u32_e32 v229, 0xffffff74, v1
	v_min_i32_e32 v229, 0x10400, v229
	v_add_u32_e32 v230, 0xffffff40, v1
	v_min_i32_e32 v230, 0x10400, v230
	v_add_u32_e32 v231, 0xffffff3c, v1
	v_min_i32_e32 v231, 0x10400, v231
	v_add_u32_e32 v232, 0xffffff38, v1
	v_min_i32_e32 v232, 0x10400, v232
	v_add_u32_e32 v233, 0xffffff34, v1
	v_min_i32_e32 v233, 0x10400, v233
	ds_read_b32 v218, v218
	ds_read_b32 v219, v219
	ds_read_b32 v220, v220
	ds_read_b32 v221, v221
	ds_read_b32 v222, v222
	ds_read_b32 v223, v223
	ds_read_b32 v224, v224
	ds_read_b32 v225, v225
	ds_read_b32 v226, v226
	ds_read_b32 v227, v227
	ds_read_b32 v228, v228
	ds_read_b32 v229, v229
	ds_read_b32 v230, v230
	ds_read_b32 v231, v231
	ds_read_b32 v232, v232
	ds_read_b32 v233, v233
	s_branch .Latt_t2_a_bc_a_done

; __device__ __forceinline__ unsigned cvt_pk_bf16(float lo, float hi) { unsigned r; asm volatile("v_cvt_pk_bf16_f32 %0, %1, %2" : "=v"(r) : "v"(lo), "v"(hi)); return r; }
; __device__ __forceinline__ void attn_softmax(f32x4 (&sc)[4], float& m_run, float& l_run, f32x4 (&o)[8], const int j, const int tq, const int g, const LAS float* tb, bf16x8 (&pb)[2]) {
;     ...
;     mx = fmaxf(mx, __shfl_xor(mx, 16)); mx = fmaxf(mx, __shfl_xor(mx, 32));
;     const float alpha = __builtin_amdgcn_exp2f(m_run - mx); m_run = mx;
;     float ls = 0.f;
; #pragma unroll
;     for (int mt = 0; mt < 4; ++mt)
; #pragma unroll
;         for (int e = 0; e < 4; ++e) { sc[mt][e] = __builtin_amdgcn_exp2f(sc[mt][e] - mx); ls += sc[mt][e]; }
;     l_run = l_run * alpha + ls;
;     if (__builtin_amdgcn_ballot_w64(alpha != 1.0f) != 0ull) {
; #pragma unroll
;         for (int cc = 0; cc < 8; ++cc) o[cc] *= alpha;
;     }
; #pragma unroll
;     for (int s2 = 0; s2 < 2; ++s2) { u32x4 pw; pw.x = cvt_pk_bf16(sc[2 * s2][0], sc[2 * s2][1]); pw.y = cvt_pk_bf16(sc[2 * s2][2], sc[2 * s2][3]);
;         pw.z = cvt_pk_bf16(sc[2 * s2 + 1][0], sc[2 * s2 + 1][1]); pw.w = cvt_pk_bf16(sc[2 * s2 + 1][2], sc[2 * s2 + 1][3]); pb[s2] = __builtin_bit_cast(bf16x8, pw); }
.Latt_t2_a_sm_a_fdone:
	v_add_u32_e32 v172, v192, v193
	v_add_u32_e32 v173, v192, v195
	v_add_u32_e32 v174, v192, v197
	v_add_u32_e32 v175, v192, v199
	v_add_u32_e32 v176, v192, v201
	v_add_u32_e32 v177, v192, v203
	v_add_u32_e32 v178, v192, v205
	v_add_u32_e32 v179, v192, v207
	ds_read_b64_tr_b16 v[218:219], v172 offset:49152
	ds_read_b64_tr_b16 v[220:221], v172 offset:53248
	ds_read_b64_tr_b16 v[222:223], v173 offset:49152
	ds_read_b64_tr_b16 v[224:225], v173 offset:53248
	ds_read_b64_tr_b16 v[226:227], v174 offset:49152
	ds_read_b64_tr_b16 v[228:229], v174 offset:53248
	ds_read_b64_tr_b16 v[230:231], v175 offset:49152
	ds_read_b64_tr_b16 v[232:233], v175 offset:53248
	ds_read_b64_tr_b16 v[234:235], v176 offset:49152
	ds_read_b64_tr_b16 v[236:237], v176 offset:53248
	ds_read_b64_tr_b16 v[238:239], v177 offset:49152
	ds_read_b64_tr_b16 v[240:241], v177 offset:53248
	ds_read_b64_tr_b16 v[242:243], v178 offset:49152
	ds_read_b64_tr_b16 v[244:245], v178 offset:53248
	v_max3_f32 v1, v217, v132, v133
	v_max3_f32 v1, v1, v134, v135
	v_max3_f32 v1, v1, v136, v137
	v_max3_f32 v1, v1, v138, v139
	v_max3_f32 v1, v1, v140, v141
	v_max3_f32 v1, v1, v142, v143
	v_max3_f32 v1, v1, v144, v145
	v_max3_f32 v1, v1, v146, v147
	v_mov_b32_e32 v3, v1
	s_nop 1
	v_permlane16_swap_b32_e32 v3, v1
	v_max_f32_e32 v1, v1, v3
	v_mov_b32_e32 v3, v1
	s_nop 1
	v_permlane32_swap_b32_e32 v3, v1
	v_max_f32_e32 v215, v1, v3
	v_sub_f32_e32 v1, v217, v215
	v_exp_f32_e32 v2, v1
	v_mov_b32_e32 v180, v215
	v_cmp_neq_f32_e32 vcc, 1.0, v2
	s_cbranch_vccz .Latt_t2_a_sm_a_norescale
	v_pk_mul_f32 v[112:113], v[112:113], v[2:3] op_sel_hi:[1,0]
	v_pk_mul_f32 v[114:115], v[114:115], v[2:3] op_sel_hi:[1,0]
	v_pk_mul_f32 v[104:105], v[104:105], v[2:3] op_sel_hi:[1,0]
	v_pk_mul_f32 v[106:107], v[106:107], v[2:3] op_sel_hi:[1,0]
	v_pk_mul_f32 v[96:97], v[96:97], v[2:3] op_sel_hi:[1,0]
	v_pk_mul_f32 v[98:99], v[98:99], v[2:3] op_sel_hi:[1,0]
	v_pk_mul_f32 v[88:89], v[88:89], v[2:3] op_sel_hi:[1,0]
	v_pk_mul_f32 v[90:91], v[90:91], v[2:3] op_sel_hi:[1,0]
	v_pk_mul_f32 v[80:81], v[80:81], v[2:3] op_sel_hi:[1,0]
	v_pk_mul_f32 v[82:83], v[82:83], v[2:3] op_sel_hi:[1,0]
	v_pk_mul_f32 v[64:65], v[64:65], v[2:3] op_sel_hi:[1,0]
	v_pk_mul_f32 v[66:67], v[66:67], v[2:3] op_sel_hi:[1,0]
	v_pk_mul_f32 v[52:53], v[52:53], v[2:3] op_sel_hi:[1,0]
	v_pk_mul_f32 v[54:55], v[54:55], v[2:3] op_sel_hi:[1,0]
	v_pk_mul_f32 v[40:41], v[40:41], v[2:3] op_sel_hi:[1,0]
	v_pk_mul_f32 v[42:43], v[42:43], v[2:3] op_sel_hi:[1,0]
.Latt_t2_a_sm_a_norescale:
	v_pk_add_f32 v[132:133], v[132:133], v[180:181] op_sel_hi:[1,0] neg_lo:[0,1] neg_hi:[0,1]
	v_pk_add_f32 v[134:135], v[134:135], v[180:181] op_sel_hi:[1,0] neg_lo:[0,1] neg_hi:[0,1]
	v_pk_add_f32 v[136:137], v[136:137], v[180:181] op_sel_hi:[1,0] neg_lo:[0,1] neg_hi:[0,1]
	v_pk_add_f32 v[138:139], v[138:139], v[180:181] op_sel_hi:[1,0] neg_lo:[0,1] neg_hi:[0,1]
	v_pk_add_f32 v[140:141], v[140:141], v[180:181] op_sel_hi:[1,0] neg_lo:[0,1] neg_hi:[0,1]
	v_pk_add_f32 v[142:143], v[142:143], v[180:181] op_sel_hi:[1,0] neg_lo:[0,1] neg_hi:[0,1]
	v_pk_add_f32 v[144:145], v[144:145], v[180:181] op_sel_hi:[1,0] neg_lo:[0,1] neg_hi:[0,1]
	v_pk_add_f32 v[146:147], v[146:147], v[180:181] op_sel_hi:[1,0] neg_lo:[0,1] neg_hi:[0,1]
	v_exp_f32_e32 v132, v132
	v_exp_f32_e32 v133, v133
	v_exp_f32_e32 v134, v134
	v_add_f32_e32 v167, v132, v133
	v_exp_f32_e32 v135, v135
	v_add_f32_e32 v167, v134, v167
	v_exp_f32_e32 v136, v136
	v_add_f32_e32 v167, v135, v167
	v_exp_f32_e32 v137, v137
	v_add_f32_e32 v167, v136, v167
	v_exp_f32_e32 v138, v138
	v_add_f32_e32 v167, v137, v167
	v_exp_f32_e32 v139, v139
	v_add_f32_e32 v167, v138, v167
	v_exp_f32_e32 v140, v140
	v_add_f32_e32 v167, v139, v167
	v_exp_f32_e32 v141, v141
	v_add_f32_e32 v167, v140, v167
	v_exp_f32_e32 v142, v142
	v_add_f32_e32 v167, v141, v167
	v_exp_f32_e32 v143, v143
	v_add_f32_e32 v167, v142, v167
	v_exp_f32_e32 v144, v144
	v_add_f32_e32 v167, v143, v167
	v_exp_f32_e32 v145, v145
	v_add_f32_e32 v167, v144, v167
	v_exp_f32_e32 v146, v146
	v_add_f32_e32 v167, v145, v167
	v_exp_f32_e32 v147, v147
	v_add_f32_e32 v167, v146, v167
	s_nop 0
	v_add_f32_e32 v167, v147, v167
	v_fma_f32 v213, v213, v2, v167
	v_cvt_pk_bf16_f32 v132, v132, v133
	v_cvt_pk_bf16_f32 v133, v134, v135
	v_cvt_pk_bf16_f32 v134, v136, v137
	v_cvt_pk_bf16_f32 v135, v138, v139
	v_cvt_pk_bf16_f32 v136, v140, v141
	v_cvt_pk_bf16_f32 v137, v142, v143
	v_cvt_pk_bf16_f32 v138, v144, v145
	v_cvt_pk_bf16_f32 v139, v146, v147
	s_waitcnt lgkmcnt(12)
	v_mfma_f32_16x16x32_bf16 v[112:115], v[218:221], v[132:135], v[112:115]
	ds_read_b64_tr_b16 v[218:219], v179 offset:49152
	ds_read_b64_tr_b16 v[220:221], v179 offset:53248
	s_waitcnt lgkmcnt(12)
	v_mfma_f32_16x16x32_bf16 v[104:107], v[222:225], v[132:135], v[104:107]
	ds_read_b64_tr_b16 v[222:223], v172 offset:57344
	ds_read_b64_tr_b16 v[224:225], v172 offset:61440
	s_waitcnt lgkmcnt(12)
	v_mfma_f32_16x16x32_bf16 v[96:99], v[226:229], v[132:135], v[96:99]
	ds_read_b64_tr_b16 v[226:227], v173 offset:57344
	ds_read_b64_tr_b16 v[228:229], v173 offset:61440
	s_waitcnt lgkmcnt(12)
	v_mfma_f32_16x16x32_bf16 v[88:91], v[230:233], v[132:135], v[88:91]
	ds_read_b64_tr_b16 v[230:231], v174 offset:57344
	ds_read_b64_tr_b16 v[232:233], v174 offset:61440
	s_waitcnt lgkmcnt(12)
	v_mfma_f32_16x16x32_bf16 v[80:83], v[234:237], v[132:135], v[80:83]
	ds_read_b64_tr_b16 v[234:235], v175 offset:57344
	ds_read_b64_tr_b16 v[236:237], v175 offset:61440
	s_waitcnt lgkmcnt(12)
	v_mfma_f32_16x16x32_bf16 v[64:67], v[238:241], v[132:135], v[64:67]
	ds_read_b64_tr_b16 v[238:239], v176 offset:57344
	ds_read_b64_tr_b16 v[240:241], v176 offset:61440
	s_waitcnt lgkmcnt(12)
	v_mfma_f32_16x16x32_bf16 v[52:55], v[242:245], v[132:135], v[52:55]
	ds_read_b64_tr_b16 v[242:243], v177 offset:57344
	ds_read_b64_tr_b16 v[244:245], v177 offset:61440
	s_waitcnt lgkmcnt(12)
	v_mfma_f32_16x16x32_bf16 v[40:43], v[218:221], v[132:135], v[40:43]
	ds_read_b64_tr_b16 v[218:219], v178 offset:57344
	ds_read_b64_tr_b16 v[220:221], v178 offset:61440
	s_waitcnt lgkmcnt(12)
	v_mfma_f32_16x16x32_bf16 v[112:115], v[222:225], v[136:139], v[112:115]
	ds_read_b64_tr_b16 v[222:223], v179 offset:57344
	ds_read_b64_tr_b16 v[224:225], v179 offset:61440
	s_waitcnt lgkmcnt(12)
	v_mfma_f32_16x16x32_bf16 v[104:107], v[226:229], v[136:139], v[104:107]
	s_waitcnt lgkmcnt(10)
	v_mfma_f32_16x16x32_bf16 v[96:99], v[230:233], v[136:139], v[96:99]
	s_waitcnt lgkmcnt(8)
	v_mfma_f32_16x16x32_bf16 v[88:91], v[234:237], v[136:139], v[88:91]
	s_waitcnt lgkmcnt(6)
	v_mfma_f32_16x16x32_bf16 v[80:83], v[238:241], v[136:139], v[80:83]
	s_waitcnt lgkmcnt(4)
	v_mfma_f32_16x16x32_bf16 v[64:67], v[242:245], v[136:139], v[64:67]
	s_waitcnt lgkmcnt(2)
	v_mfma_f32_16x16x32_bf16 v[52:55], v[218:221], v[136:139], v[52:55]
	s_waitcnt lgkmcnt(0)
	v_mfma_f32_16x16x32_bf16 v[40:43], v[222:225], v[136:139], v[40:43]
	v_mov_b32_e32 v214, v216
	s_andn2_b64 vcc, exec, s[46:47]
	s_cbranch_vccnz .LBB0_232
	s_branch .LBB0_514
; __device__ __forceinline__ void attn_softmax(f32x4 (&sc)[4], float& m_run, float& l_run, f32x4 (&o)[8], const int j, const int tq, const int g, const LAS float* tb, bf16x8 (&pb)[2]) {
;     ...
;     else { const int relb = tq + 64 * (8 - j) - 4 * g;
; #pragma unroll
;         for (int mt = 0; mt < 4; ++mt)
; #pragma unroll
;             for (int e = 0; e < 4; ++e) { int rel = relb - 16 * mt - e; rel = rel > 128 ? 128 : rel; sc[mt][e] = sc[mt][e] * SC + tb[rel + 128]; mx = fmaxf(mx, sc[mt][e]); } }
.Latt_t2_b:
	s_sub_i32 s36, s74, s93
	s_add_i32 s36, s36, 1
	s_add_i32 s37, s36, -1
	v_add_u32_e32 v164, v187, v189
	v_add_u32_e32 v165, v187, v190
	v_add_u32_e32 v166, v187, v191
	ds_read_b128 v[218:221], v211 offset:32768
	ds_read_b128 v[222:225], v164 offset:32768
	ds_read_b128 v[226:229], v165 offset:32768
	ds_read_b128 v[230:233], v166 offset:32768
	ds_read_b128 v[234:237], v211 offset:36864
	ds_read_b128 v[238:241], v164 offset:36864
	ds_read_b128 v[242:245], v165 offset:36864
	ds_read_b128 v[246:249], v166 offset:36864
	s_waitcnt lgkmcnt(7)
	v_mfma_f32_16x16x32_bf16 v[148:151], v[218:221], v[8:11], 0
	ds_read_b128 v[218:221], v211 offset:40960
	s_waitcnt lgkmcnt(7)
	v_mfma_f32_16x16x32_bf16 v[148:151], v[222:225], v[16:19], v[148:151]
	ds_read_b128 v[222:225], v164 offset:40960
	s_waitcnt lgkmcnt(7)
	v_mfma_f32_16x16x32_bf16 v[148:151], v[226:229], v[24:27], v[148:151]
	ds_read_b128 v[226:229], v165 offset:40960
	s_waitcnt lgkmcnt(7)
	v_mfma_f32_16x16x32_bf16 v[148:151], v[230:233], v[32:35], v[148:151]
	ds_read_b128 v[230:233], v166 offset:40960
	s_waitcnt lgkmcnt(7)
	v_mfma_f32_16x16x32_bf16 v[152:155], v[234:237], v[8:11], 0
	ds_read_b128 v[234:237], v211 offset:45056
	s_waitcnt lgkmcnt(7)
	v_mfma_f32_16x16x32_bf16 v[152:155], v[238:241], v[16:19], v[152:155]
	ds_read_b128 v[238:241], v164 offset:45056
	s_waitcnt lgkmcnt(7)
	v_mfma_f32_16x16x32_bf16 v[152:155], v[242:245], v[24:27], v[152:155]
	ds_read_b128 v[242:245], v165 offset:45056
	s_waitcnt lgkmcnt(7)
	v_mfma_f32_16x16x32_bf16 v[152:155], v[246:249], v[32:35], v[152:155]
	ds_read_b128 v[246:249], v166 offset:45056
	s_waitcnt lgkmcnt(7)
	v_mfma_f32_16x16x32_bf16 v[156:159], v[218:221], v[8:11], 0
	s_waitcnt lgkmcnt(6)
	v_mfma_f32_16x16x32_bf16 v[156:159], v[222:225], v[16:19], v[156:159]
	s_waitcnt lgkmcnt(5)
	v_mfma_f32_16x16x32_bf16 v[156:159], v[226:229], v[24:27], v[156:159]
	s_waitcnt lgkmcnt(4)
	v_mfma_f32_16x16x32_bf16 v[156:159], v[230:233], v[32:35], v[156:159]
	s_waitcnt lgkmcnt(0)
	s_cmp_gt_i32 s37, 5
	s_cbranch_scc0 .Latt_t2_b_bc_b_const
	s_mov_b32 s38, 0x10100
	v_lshl_add_u32 v1, v210, 2, s38
	v_min_i32_e32 v218, 0x10400, v1
	v_add_u32_e32 v219, 0xfffffffc, v1
	v_min_i32_e32 v219, 0x10400, v219
	v_add_u32_e32 v220, 0xfffffff8, v1
	v_min_i32_e32 v220, 0x10400, v220
	v_add_u32_e32 v221, 0xfffffff4, v1
	v_min_i32_e32 v221, 0x10400, v221
	v_add_u32_e32 v222, 0xffffffc0, v1
	v_min_i32_e32 v222, 0x10400, v222
	v_add_u32_e32 v223, 0xffffffbc, v1
	v_min_i32_e32 v223, 0x10400, v223
	v_add_u32_e32 v224, 0xffffffb8, v1
	v_min_i32_e32 v224, 0x10400, v224
	v_add_u32_e32 v225, 0xffffffb4, v1
	v_min_i32_e32 v225, 0x10400, v225
	v_add_u32_e32 v226, 0xffffff80, v1
	v_min_i32_e32 v226, 0x10400, v226
	v_add_u32_e32 v227, 0xffffff7c, v1
	v_min_i32_e32 v227, 0x10400, v227
	v_add_u32_e32 v228, 0xffffff78, v1
	v_min_i32_e32 v228, 0x10400, v228
	v_add_u32_e32 v229, 0xffffff74, v1
	v_min_i32_e32 v229, 0x10400, v229
	v_add_u32_e32 v230, 0xffffff40, v1
	v_min_i32_e32 v230, 0x10400, v230
	v_add_u32_e32 v231, 0xffffff3c, v1
	v_min_i32_e32 v231, 0x10400, v231
	v_add_u32_e32 v232, 0xffffff38, v1
	v_min_i32_e32 v232, 0x10400, v232
	v_add_u32_e32 v233, 0xffffff34, v1
	v_min_i32_e32 v233, 0x10400, v233
	ds_read_b32 v218, v218
	ds_read_b32 v219, v219
	ds_read_b32 v220, v220
	ds_read_b32 v221, v221
	ds_read_b32 v222, v222
	ds_read_b32 v223, v223
	ds_read_b32 v224, v224
	ds_read_b32 v225, v225
	ds_read_b32 v226, v226
	ds_read_b32 v227, v227
	ds_read_b32 v228, v228
	ds_read_b32 v229, v229
	ds_read_b32 v230, v230
	ds_read_b32 v231, v231
	ds_read_b32 v232, v232
	ds_read_b32 v233, v233
	s_branch .Latt_t2_b_bc_b_done

; __device__ __forceinline__ unsigned cvt_pk_bf16(float lo, float hi) { unsigned r; asm volatile("v_cvt_pk_bf16_f32 %0, %1, %2" : "=v"(r) : "v"(lo), "v"(hi)); return r; }
; #define ATT_LOAD(u_, KR, VR) do { const long _o = (long)((u_) >> 2) * (28L << 16) + ((u_) & 1) * 32768 + (((u_) >> 1) & 1) * 4096; _Pragma("unroll") for (int _i = 0; _i < 2; ++_i) { \
;         KR[_i] = *(const u32x4*)(kb0 + _o + _i * 16384); VR[_i] = *(const u32x4*)(vb0 + _o + _i * 16384); } } while (0)
; #define ATT_STORE(buf_, KR, VR) do { _Pragma("unroll") for (int _i = 0; _i < 2; ++_i) { const unsigned ob_ = off_b(srow, sch + 8 * _i); \
;         *(LAS u32x4*)(lds + (buf_) * 32768 + ob_) = KR[_i]; *(LAS u32x4*)(lds + (buf_) * 32768 + 16384 + ob_) = VR[_i]; } } while (0)
; __device__ __forceinline__ void attn_softmax(f32x4 (&sc)[4], float& m_run, float& l_run, f32x4 (&o)[8], const int j, const int tq, const int g, const LAS float* tb, bf16x8 (&pb)[2]) {
;     ...
;     const float alpha = __builtin_amdgcn_exp2f(m_run - mx); m_run = mx;
;     float ls = 0.f;
; #pragma unroll
;     for (int mt = 0; mt < 4; ++mt)
; #pragma unroll
;         for (int e = 0; e < 4; ++e) { sc[mt][e] = __builtin_amdgcn_exp2f(sc[mt][e] - mx); ls += sc[mt][e]; }
;     l_run = l_run * alpha + ls;
;     if (__builtin_amdgcn_ballot_w64(alpha != 1.0f) != 0ull) {
; #pragma unroll
;         for (int cc = 0; cc < 8; ++cc) o[cc] *= alpha;
;     }
; #pragma unroll
;     for (int s2 = 0; s2 < 2; ++s2) { u32x4 pw; pw.x = cvt_pk_bf16(sc[2 * s2][0], sc[2 * s2][1]); pw.y = cvt_pk_bf16(sc[2 * s2][2], sc[2 * s2][3]);
;         pw.z = cvt_pk_bf16(sc[2 * s2 + 1][0], sc[2 * s2 + 1][1]); pw.w = cvt_pk_bf16(sc[2 * s2 + 1][2], sc[2 * s2 + 1][3]); pb[s2] = __builtin_bit_cast(bf16x8, pw); }
; __device__ void attn_quad(const bf16_t* proj, const float* rel_bias, bf16_t* ycat, int quad, LAS unsigned char* lds, const int WID) {
;     ...
;     ATT_LOAD(u0, kr0, vr0); ATT_LOAD(u0 + 1, kr1, vr1); ATT_STORE(0, kr0, vr0);
;     __syncthreads();
;     int buf = 0;
;     for (int u = u0; u < 12; u += 2) {
;         if (u + 2 < 12) ATT_LOAD(u + 2, kr0, vr0);
;         ATT_COMPUTE(u);
;         ATT_STORE(buf ^ 1, kr1, vr1);
;         __syncthreads(); buf ^= 1;
;         if (u + 3 < 12) ATT_LOAD(u + 3, kr1, vr1);
;         ATT_COMPUTE(u + 1);
;         if (u + 2 < 12) ATT_STORE(buf ^ 1, kr0, vr0);
;         __syncthreads(); buf ^= 1;
.Latt_t2_b_sm_b_norescale:
	v_pk_add_f32 v[148:149], v[148:149], v[180:181] op_sel_hi:[1,0] neg_lo:[0,1] neg_hi:[0,1]
	v_pk_add_f32 v[150:151], v[150:151], v[180:181] op_sel_hi:[1,0] neg_lo:[0,1] neg_hi:[0,1]
	v_pk_add_f32 v[152:153], v[152:153], v[180:181] op_sel_hi:[1,0] neg_lo:[0,1] neg_hi:[0,1]
	v_pk_add_f32 v[154:155], v[154:155], v[180:181] op_sel_hi:[1,0] neg_lo:[0,1] neg_hi:[0,1]
	v_pk_add_f32 v[156:157], v[156:157], v[180:181] op_sel_hi:[1,0] neg_lo:[0,1] neg_hi:[0,1]
	v_pk_add_f32 v[158:159], v[158:159], v[180:181] op_sel_hi:[1,0] neg_lo:[0,1] neg_hi:[0,1]
	v_pk_add_f32 v[160:161], v[160:161], v[180:181] op_sel_hi:[1,0] neg_lo:[0,1] neg_hi:[0,1]
	v_pk_add_f32 v[162:163], v[162:163], v[180:181] op_sel_hi:[1,0] neg_lo:[0,1] neg_hi:[0,1]
	v_exp_f32_e32 v148, v148
	v_exp_f32_e32 v149, v149
	v_exp_f32_e32 v150, v150
	v_add_f32_e32 v167, v148, v149
	v_exp_f32_e32 v151, v151
	v_add_f32_e32 v167, v150, v167
	v_exp_f32_e32 v152, v152
	v_add_f32_e32 v167, v151, v167
	v_exp_f32_e32 v153, v153
	v_add_f32_e32 v167, v152, v167
	v_exp_f32_e32 v154, v154
	v_add_f32_e32 v167, v153, v167
	v_exp_f32_e32 v155, v155
	v_add_f32_e32 v167, v154, v167
	v_exp_f32_e32 v156, v156
	v_add_f32_e32 v167, v155, v167
	v_exp_f32_e32 v157, v157
	v_add_f32_e32 v167, v156, v167
	v_exp_f32_e32 v158, v158
	v_add_f32_e32 v167, v157, v167
	v_exp_f32_e32 v159, v159
	v_add_f32_e32 v167, v158, v167
	v_exp_f32_e32 v160, v160
	v_add_f32_e32 v167, v159, v167
	v_exp_f32_e32 v161, v161
	v_add_f32_e32 v167, v160, v167
	v_exp_f32_e32 v162, v162
	v_add_f32_e32 v167, v161, v167
	v_exp_f32_e32 v163, v163
	v_add_f32_e32 v167, v162, v167
	s_nop 0
	v_add_f32_e32 v167, v163, v167
	v_fma_f32 v212, v212, v2, v167
	v_cvt_pk_bf16_f32 v148, v148, v149
	v_cvt_pk_bf16_f32 v149, v150, v151
	v_cvt_pk_bf16_f32 v150, v152, v153
	v_cvt_pk_bf16_f32 v151, v154, v155
	v_cvt_pk_bf16_f32 v152, v156, v157
	v_cvt_pk_bf16_f32 v153, v158, v159
	v_cvt_pk_bf16_f32 v154, v160, v161
	v_cvt_pk_bf16_f32 v155, v162, v163
	s_waitcnt lgkmcnt(12)
	v_mfma_f32_16x16x32_bf16 v[108:111], v[218:221], v[148:151], v[108:111]
	ds_read_b64_tr_b16 v[218:219], v179 offset:49152
	ds_read_b64_tr_b16 v[220:221], v179 offset:53248
	s_waitcnt lgkmcnt(12)
	v_mfma_f32_16x16x32_bf16 v[100:103], v[222:225], v[148:151], v[100:103]
	ds_read_b64_tr_b16 v[222:223], v172 offset:57344
	ds_read_b64_tr_b16 v[224:225], v172 offset:61440
	s_waitcnt lgkmcnt(12)
	v_mfma_f32_16x16x32_bf16 v[92:95], v[226:229], v[148:151], v[92:95]
	ds_read_b64_tr_b16 v[226:227], v173 offset:57344
	ds_read_b64_tr_b16 v[228:229], v173 offset:61440
	s_waitcnt lgkmcnt(12)
	v_mfma_f32_16x16x32_bf16 v[84:87], v[230:233], v[148:151], v[84:87]
	ds_read_b64_tr_b16 v[230:231], v174 offset:57344
	ds_read_b64_tr_b16 v[232:233], v174 offset:61440
	s_waitcnt lgkmcnt(12)
	v_mfma_f32_16x16x32_bf16 v[76:79], v[234:237], v[148:151], v[76:79]
	ds_read_b64_tr_b16 v[234:235], v175 offset:57344
	ds_read_b64_tr_b16 v[236:237], v175 offset:61440
	s_waitcnt lgkmcnt(12)
	v_mfma_f32_16x16x32_bf16 v[60:63], v[238:241], v[148:151], v[60:63]
	ds_read_b64_tr_b16 v[238:239], v176 offset:57344
	ds_read_b64_tr_b16 v[240:241], v176 offset:61440
	s_waitcnt lgkmcnt(12)
	v_mfma_f32_16x16x32_bf16 v[48:51], v[242:245], v[148:151], v[48:51]
	ds_read_b64_tr_b16 v[242:243], v177 offset:57344
	ds_read_b64_tr_b16 v[244:245], v177 offset:61440
	s_waitcnt lgkmcnt(12)
	v_mfma_f32_16x16x32_bf16 v[36:39], v[218:221], v[148:151], v[36:39]
	ds_read_b64_tr_b16 v[218:219], v178 offset:57344
	ds_read_b64_tr_b16 v[220:221], v178 offset:61440
	s_waitcnt lgkmcnt(12)
	v_mfma_f32_16x16x32_bf16 v[108:111], v[222:225], v[152:155], v[108:111]
	ds_read_b64_tr_b16 v[222:223], v179 offset:57344
	ds_read_b64_tr_b16 v[224:225], v179 offset:61440
	s_waitcnt lgkmcnt(12)
	v_mfma_f32_16x16x32_bf16 v[100:103], v[226:229], v[152:155], v[100:103]
	s_waitcnt lgkmcnt(10)
	v_mfma_f32_16x16x32_bf16 v[92:95], v[230:233], v[152:155], v[92:95]
	s_waitcnt lgkmcnt(8)
	v_mfma_f32_16x16x32_bf16 v[84:87], v[234:237], v[152:155], v[84:87]
	s_waitcnt lgkmcnt(6)
	v_mfma_f32_16x16x32_bf16 v[76:79], v[238:241], v[152:155], v[76:79]
	s_waitcnt lgkmcnt(4)
	v_mfma_f32_16x16x32_bf16 v[60:63], v[242:245], v[152:155], v[60:63]
	s_waitcnt lgkmcnt(2)
	v_mfma_f32_16x16x32_bf16 v[48:51], v[218:221], v[152:155], v[48:51]
	s_waitcnt lgkmcnt(0)
	v_mfma_f32_16x16x32_bf16 v[36:39], v[222:225], v[152:155], v[36:39]
	v_mov_b32_e32 v215, v217
	s_andn2_b64 vcc, exec, s[46:47]
	s_cbranch_vccnz .LBB0_232
	s_branch .LBB0_514
.LBB0_514:
	ds_write_b128 v185, v[44:47]
	ds_write_b128 v185, v[56:59] offset:16384
	ds_write_b128 v186, v[68:71]
	ds_write_b128 v186, v[72:75] offset:16384
	s_branch .LBB0_232
.LBB0_533:
	s_waitcnt vmcnt(0)
	s_and_b64 vcc, exec, s[82:83]
	s_barrier
	s_cbranch_vccz .LBB0_587
	v_mbcnt_lo_u32_b32 v0, -1, 0
	v_mbcnt_hi_u32_b32 v0, -1, v0
	s_nop 0
	v_cmp_eq_u32_e32 vcc, 0, v0
	s_and_saveexec_b64 s[2:3], vcc
	s_cbranch_execz .LBB0_586
	s_add_i32 s4, 0, 0x253f0
	v_mov_b32_e32 v0, s4
	s_waitcnt vmcnt(0) expcnt(0) lgkmcnt(0)
	ds_read_b32 v2, v0
	s_add_i32 s4, 0, 0x253f4
	v_mov_b32_e32 v0, s4
	ds_read_b32 v0, v0
	s_waitcnt lgkmcnt(1)
	v_cmp_ne_u32_e32 vcc, 0, v2
	s_cbranch_vccnz .LBB0_550
	s_mov_b32 s12, 1
	v_mov_b32_e32 v16, 0
	s_branch .LBB0_538
